# v43 + G1/F1 sites: peeled first half K-iteration of non-first units with vmcnt(8+S) so epilogue stores need not be acked before the first two barriers
# speedup vs baseline: 1.0062x; 1.0062x over previous
.LBB0_388:
	v_bfe_u32 v18, v8, 4, 2
	v_and_b32_e32 v9, 15, v8
	v_lshlrev_b32_e32 v20, 4, v18
	v_lshlrev_b32_e32 v8, 2, v8
	v_mov_b32_e32 v133, v203
	s_and_b32 s38, s0, 3
	v_lshl_or_b32 v150, s1, 6, v9
	v_lshl_or_b32 v9, v9, 6, v20
	s_lshl_b32 s0, s1, 13
	v_and_b32_e32 v8, 32, v8
	v_lshl_add_u64 v[10:11], s[26:27], 0, v[132:133]
	v_mov_b32_e32 v137, v203
	v_bitop3_b32 v20, v9, s0, v8 bitop3:0xde
	s_lshl_b32 s0, s38, 12
	v_lshl_add_u64 v[12:13], s[26:27], 0, v[136:137]
	v_mov_b32_e32 v131, v203
	v_bitop3_b32 v151, v9, s0, v8 bitop3:0xde
	v_add_u32_e32 v151, 0x10000, v151
	s_add_i32 m0, s9, 0x18000
	v_lshl_add_u64 v[8:9], v[10:11], 0, s[80:81]
	v_lshl_add_u64 v[14:15], s[24:25], 0, v[130:131]
	v_mov_b32_e32 v135, v203
	s_waitcnt vmcnt(2)
	s_barrier
	global_load_lds_dwordx4 v[8:9], off
	v_lshl_add_u64 v[8:9], v[12:13], 0, s[80:81]
	s_add_i32 m0, s9, 0x1a000
	s_add_i32 s39, s9, 0x8000
	s_add_i32 s40, s9, 0xa000
	v_lshl_add_u64 v[16:17], s[24:25], 0, v[134:135]
	global_load_lds_dwordx4 v[8:9], off
	v_lshl_add_u64 v[8:9], v[14:15], 0, s[80:81]
	s_mov_b32 m0, s39
	s_add_u32 s0, s26, 0x80080
	global_load_lds_dwordx4 v[8:9], off
	v_lshl_add_u64 v[8:9], v[16:17], 0, s[80:81]
	s_mov_b32 m0, s40
	s_addc_u32 s1, s27, 0
	global_load_lds_dwordx4 v[8:9], off
	s_add_i32 m0, s9, 0x1c000
	v_lshl_add_u64 v[8:9], s[0:1], 0, v[132:133]
	global_load_lds_dwordx4 v[8:9], off
	v_lshl_add_u64 v[8:9], s[0:1], 0, v[136:137]
	s_add_i32 m0, s9, 0x1e000
	v_lshlrev_b32_e32 v19, 3, v18
	global_load_lds_dwordx4 v[8:9], off
	v_lshlrev_b32_e32 v8, 15, v2
	v_and_b32_e32 v8, 0xffff0000, v8
	v_lshl_add_u32 v3, v3, 12, v8
	v_and_b32_e32 v2, 1, v2
	v_lshl_or_b32 v2, v2, 6, v3
	v_lshl_add_u32 v138, v4, 1, v2
	v_lshlrev_b32_e32 v2, 15, v5
	v_and_b32_e32 v2, 0xffff0000, v2
	s_waitcnt vmcnt(6)
	v_lshl_add_u32 v2, v6, 12, v2
	v_and_b32_e32 v3, 1, v5
	s_cmpk_lt_u32 s2, 0x100
	v_lshl_or_b32 v2, v3, 6, v2
	v_lshl_or_b32 v152, s38, 5, v19
	s_cselect_b64 s[14:15], -1, 0
	s_mov_b32 s41, 0
	v_cmp_eq_u32_e64 s[2:3], 0, v18
	v_mov_b32_e32 v139, v203
	v_lshl_add_u32 v140, v7, 1, v2
	v_mov_b32_e32 v141, v203
	v_add_u32_e32 v153, 0, v20
	s_barrier
	s_mov_b32 s101, 0
	s_branch .LBB0_391

.LBB0_393:
	s_ashr_i32 s19, s18, 31
	s_lshl_b64 s[0:1], s[18:19], 20
	s_add_u32 s20, s42, s0
	s_addc_u32 s21, s43, s1
	s_and_b64 s[0:1], s[4:5], exec
	s_cselect_b32 s7, s21, s25
	s_cselect_b32 s19, s20, s24
	s_ashr_i32 s17, s16, 31
	s_lshl_b64 s[0:1], s[16:17], 20
	s_add_u32 s22, s30, s0
	s_addc_u32 s23, s31, s1
	s_and_b64 s[0:1], s[4:5], exec
	s_cselect_b32 s17, s23, s27
	s_cselect_b32 s49, s22, s26
	s_add_u32 s24, s24, 0x80080
	s_addc_u32 s25, s25, 0
	s_add_u32 s58, s26, 0x100
	v_mov_b32_e32 v2, 0
	s_addc_u32 s59, s27, 0
	s_mov_b32 s60, -2
	v_mov_b32_e32 v3, v2
	s_waitcnt lgkmcnt(0)
	v_pk_mov_b32 v[4:5], v[2:3], v[2:3] op_sel:[0,1]
	v_pk_mov_b32 v[6:7], v[2:3], v[2:3] op_sel:[0,1]
	v_pk_mov_b32 v[8:9], v[2:3], v[2:3] op_sel:[0,1]
	v_pk_mov_b32 v[18:19], v[2:3], v[2:3] op_sel:[0,1]
	v_pk_mov_b32 v[20:21], v[2:3], v[2:3] op_sel:[0,1]
	v_pk_mov_b32 v[22:23], v[2:3], v[2:3] op_sel:[0,1]
	v_pk_mov_b32 v[24:25], v[2:3], v[2:3] op_sel:[0,1]
	v_pk_mov_b32 v[34:35], v[2:3], v[2:3] op_sel:[0,1]
	v_pk_mov_b32 v[36:37], v[2:3], v[2:3] op_sel:[0,1]
	v_pk_mov_b32 v[38:39], v[2:3], v[2:3] op_sel:[0,1]
	v_pk_mov_b32 v[40:41], v[2:3], v[2:3] op_sel:[0,1]
	v_pk_mov_b32 v[50:51], v[2:3], v[2:3] op_sel:[0,1]
	v_pk_mov_b32 v[52:53], v[2:3], v[2:3] op_sel:[0,1]
	v_pk_mov_b32 v[54:55], v[2:3], v[2:3] op_sel:[0,1]
	v_pk_mov_b32 v[56:57], v[2:3], v[2:3] op_sel:[0,1]
	v_pk_mov_b32 v[10:11], v[2:3], v[2:3] op_sel:[0,1]
	v_pk_mov_b32 v[12:13], v[2:3], v[2:3] op_sel:[0,1]
	v_pk_mov_b32 v[14:15], v[2:3], v[2:3] op_sel:[0,1]
	v_pk_mov_b32 v[16:17], v[2:3], v[2:3] op_sel:[0,1]
	v_pk_mov_b32 v[26:27], v[2:3], v[2:3] op_sel:[0,1]
	v_pk_mov_b32 v[28:29], v[2:3], v[2:3] op_sel:[0,1]
	v_pk_mov_b32 v[30:31], v[2:3], v[2:3] op_sel:[0,1]
	v_pk_mov_b32 v[32:33], v[2:3], v[2:3] op_sel:[0,1]
	v_pk_mov_b32 v[42:43], v[2:3], v[2:3] op_sel:[0,1]
	v_pk_mov_b32 v[44:45], v[2:3], v[2:3] op_sel:[0,1]
	v_pk_mov_b32 v[46:47], v[2:3], v[2:3] op_sel:[0,1]
	v_pk_mov_b32 v[48:49], v[2:3], v[2:3] op_sel:[0,1]
	v_pk_mov_b32 v[58:59], v[2:3], v[2:3] op_sel:[0,1]
	v_pk_mov_b32 v[60:61], v[2:3], v[2:3] op_sel:[0,1]
	v_pk_mov_b32 v[62:63], v[2:3], v[2:3] op_sel:[0,1]
	v_pk_mov_b32 v[64:65], v[2:3], v[2:3] op_sel:[0,1]
	v_pk_mov_b32 v[66:67], v[2:3], v[2:3] op_sel:[0,1]
	v_pk_mov_b32 v[68:69], v[2:3], v[2:3] op_sel:[0,1]
	v_pk_mov_b32 v[70:71], v[2:3], v[2:3] op_sel:[0,1]
	v_pk_mov_b32 v[72:73], v[2:3], v[2:3] op_sel:[0,1]
	v_pk_mov_b32 v[82:83], v[2:3], v[2:3] op_sel:[0,1]
	v_pk_mov_b32 v[84:85], v[2:3], v[2:3] op_sel:[0,1]
	v_pk_mov_b32 v[86:87], v[2:3], v[2:3] op_sel:[0,1]
	v_pk_mov_b32 v[88:89], v[2:3], v[2:3] op_sel:[0,1]
	v_pk_mov_b32 v[98:99], v[2:3], v[2:3] op_sel:[0,1]
	v_pk_mov_b32 v[100:101], v[2:3], v[2:3] op_sel:[0,1]
	v_pk_mov_b32 v[102:103], v[2:3], v[2:3] op_sel:[0,1]
	v_pk_mov_b32 v[104:105], v[2:3], v[2:3] op_sel:[0,1]
	v_pk_mov_b32 v[114:115], v[2:3], v[2:3] op_sel:[0,1]
	v_pk_mov_b32 v[116:117], v[2:3], v[2:3] op_sel:[0,1]
	v_pk_mov_b32 v[118:119], v[2:3], v[2:3] op_sel:[0,1]
	v_pk_mov_b32 v[120:121], v[2:3], v[2:3] op_sel:[0,1]
	v_pk_mov_b32 v[74:75], v[2:3], v[2:3] op_sel:[0,1]
	v_pk_mov_b32 v[76:77], v[2:3], v[2:3] op_sel:[0,1]
	v_pk_mov_b32 v[78:79], v[2:3], v[2:3] op_sel:[0,1]
	v_pk_mov_b32 v[80:81], v[2:3], v[2:3] op_sel:[0,1]
	v_pk_mov_b32 v[90:91], v[2:3], v[2:3] op_sel:[0,1]
	v_pk_mov_b32 v[92:93], v[2:3], v[2:3] op_sel:[0,1]
	v_pk_mov_b32 v[94:95], v[2:3], v[2:3] op_sel:[0,1]
	v_pk_mov_b32 v[96:97], v[2:3], v[2:3] op_sel:[0,1]
	v_pk_mov_b32 v[106:107], v[2:3], v[2:3] op_sel:[0,1]
	v_pk_mov_b32 v[108:109], v[2:3], v[2:3] op_sel:[0,1]
	v_pk_mov_b32 v[110:111], v[2:3], v[2:3] op_sel:[0,1]
	v_pk_mov_b32 v[112:113], v[2:3], v[2:3] op_sel:[0,1]
	v_pk_mov_b32 v[122:123], v[2:3], v[2:3] op_sel:[0,1]
	v_pk_mov_b32 v[124:125], v[2:3], v[2:3] op_sel:[0,1]
	v_pk_mov_b32 v[126:127], v[2:3], v[2:3] op_sel:[0,1]
	v_pk_mov_b32 v[128:129], v[2:3], v[2:3] op_sel:[0,1]
	s_cmp_eq_u32 s101, 0x80000001
	s_cbranch_scc0 .LBB0_394
	s_add_u32 s0, s24, 0xfff80080
	s_addc_u32 s1, s25, -1
	s_add_i32 s33, 0, 0x10000
	s_cmp_eq_u32 s60, 28
	s_cselect_b32 s29, s7, s1
	s_cselect_b32 s28, s19, s0
	s_cselect_b32 s27, s17, s59
	s_cselect_b32 s26, s49, s58
	s_add_i32 s55, 0, 0x14000
	ds_read_b128 v[142:145], v151
	ds_read_b128 v[146:149], v151 offset:1024
	ds_read_b128 v[154:157], v151 offset:2048
	ds_read_b128 v[158:161], v151 offset:3072
	ds_read_b128 v[162:165], v151 offset:16384
	ds_read_b128 v[166:169], v151 offset:17408
	ds_read_b128 v[170:173], v151 offset:18432
	ds_read_b128 v[174:177], v151 offset:19456
	s_add_i32 m0, s9, 0xc000
	ds_read_b128 v[178:181], v153
	ds_read_b128 v[182:185], v153 offset:1024
	ds_read_b128 v[186:189], v153 offset:2048
	ds_read_b128 v[190:193], v153 offset:3072
	ds_read_b128 v[194:197], v153 offset:4096
	ds_read_b128 v[198:201], v153 offset:5120
	ds_read_b128 v[208:211], v153 offset:6144
	ds_read_b128 v[212:215], v153 offset:7168
	global_load_lds_dwordx4 v138, s[24:25]
	s_add_i32 m0, s9, 0xe000
	s_nop 0
	global_load_lds_dwordx4 v140, s[24:25]
	s_waitcnt vmcnt(24)
	s_waitcnt lgkmcnt(0)
	s_setprio 1
	s_barrier
	v_mfma_f32_16x16x32_bf16 v[126:129], v[142:145], v[178:181], v[126:129]
	v_mfma_f32_16x16x32_bf16 v[122:125], v[154:157], v[178:181], v[122:125]
	v_mfma_f32_16x16x32_bf16 v[110:113], v[142:145], v[186:189], v[110:113]
	v_mfma_f32_16x16x32_bf16 v[106:109], v[154:157], v[186:189], v[106:109]
	v_mfma_f32_16x16x32_bf16 v[94:97], v[142:145], v[194:197], v[94:97]
	v_mfma_f32_16x16x32_bf16 v[90:93], v[154:157], v[194:197], v[90:93]
	v_mfma_f32_16x16x32_bf16 v[78:81], v[142:145], v[208:211], v[78:81]
	v_mfma_f32_16x16x32_bf16 v[74:77], v[154:157], v[208:211], v[74:77]
	v_mfma_f32_16x16x32_bf16 v[126:129], v[146:149], v[182:185], v[126:129]
	v_mfma_f32_16x16x32_bf16 v[122:125], v[158:161], v[182:185], v[122:125]
	v_mfma_f32_16x16x32_bf16 v[110:113], v[146:149], v[190:193], v[110:113]
	v_mfma_f32_16x16x32_bf16 v[106:109], v[158:161], v[190:193], v[106:109]
	v_mfma_f32_16x16x32_bf16 v[94:97], v[146:149], v[198:201], v[94:97]
	v_mfma_f32_16x16x32_bf16 v[90:93], v[158:161], v[198:201], v[90:93]
	v_mfma_f32_16x16x32_bf16 v[78:81], v[146:149], v[212:215], v[78:81]
	v_mfma_f32_16x16x32_bf16 v[74:77], v[158:161], v[212:215], v[74:77]
	v_mfma_f32_16x16x32_bf16 v[118:121], v[162:165], v[178:181], v[118:121]
	v_mfma_f32_16x16x32_bf16 v[114:117], v[170:173], v[178:181], v[114:117]
	v_mfma_f32_16x16x32_bf16 v[102:105], v[162:165], v[186:189], v[102:105]
	v_mfma_f32_16x16x32_bf16 v[98:101], v[170:173], v[186:189], v[98:101]
	v_mfma_f32_16x16x32_bf16 v[86:89], v[162:165], v[194:197], v[86:89]
	v_mfma_f32_16x16x32_bf16 v[82:85], v[170:173], v[194:197], v[82:85]
	v_mfma_f32_16x16x32_bf16 v[70:73], v[162:165], v[208:211], v[70:73]
	v_mfma_f32_16x16x32_bf16 v[66:69], v[170:173], v[208:211], v[66:69]
	v_mfma_f32_16x16x32_bf16 v[118:121], v[166:169], v[182:185], v[118:121]
	v_mfma_f32_16x16x32_bf16 v[114:117], v[174:177], v[182:185], v[114:117]
	v_mfma_f32_16x16x32_bf16 v[102:105], v[166:169], v[190:193], v[102:105]
	v_mfma_f32_16x16x32_bf16 v[98:101], v[174:177], v[190:193], v[98:101]
	v_mfma_f32_16x16x32_bf16 v[86:89], v[166:169], v[198:201], v[86:89]
	v_mfma_f32_16x16x32_bf16 v[82:85], v[174:177], v[198:201], v[82:85]
	v_mfma_f32_16x16x32_bf16 v[70:73], v[166:169], v[212:215], v[70:73]
	v_mfma_f32_16x16x32_bf16 v[66:69], v[174:177], v[212:215], v[66:69]
	s_barrier
	s_setprio 0
	s_add_i32 s0, s33, s34
	s_mov_b32 m0, s0
	ds_read_b128 v[178:181], v153 offset:16384
	ds_read_b128 v[182:185], v153 offset:17408
	ds_read_b128 v[186:189], v153 offset:18432
	ds_read_b128 v[190:193], v153 offset:19456
	ds_read_b128 v[194:197], v153 offset:20480
	ds_read_b128 v[198:201], v153 offset:21504
	ds_read_b128 v[208:211], v153 offset:22528
	ds_read_b128 v[212:215], v153 offset:23552
	global_load_lds_dwordx4 v132, s[26:27]
	s_add_i32 m0, s0, 0x2000
	s_add_u32 s0, s26, 0x80000
	s_addc_u32 s1, s27, 0
	s_add_i32 s33, s55, s34
	global_load_lds_dwordx4 v136, s[26:27]
	s_mov_b32 m0, s33
	s_nop 0
	global_load_lds_dwordx4 v132, s[0:1]
	s_add_i32 m0, s33, 0x2000
	s_nop 0
	global_load_lds_dwordx4 v136, s[0:1]
	s_mov_b32 m0, s9
	s_nop 0
	global_load_lds_dwordx4 v130, s[28:29]
	s_mov_b32 m0, s35
	s_nop 0
	global_load_lds_dwordx4 v134, s[28:29]
	s_waitcnt vmcnt(24)
	s_waitcnt lgkmcnt(0)
	s_setprio 1
	s_barrier
	v_mfma_f32_16x16x32_bf16 v[62:65], v[142:145], v[178:181], v[62:65]
	v_mfma_f32_16x16x32_bf16 v[58:61], v[154:157], v[178:181], v[58:61]
	v_mfma_f32_16x16x32_bf16 v[46:49], v[142:145], v[186:189], v[46:49]
	v_mfma_f32_16x16x32_bf16 v[42:45], v[154:157], v[186:189], v[42:45]
	v_mfma_f32_16x16x32_bf16 v[30:33], v[142:145], v[194:197], v[30:33]
	v_mfma_f32_16x16x32_bf16 v[26:29], v[154:157], v[194:197], v[26:29]
	v_mfma_f32_16x16x32_bf16 v[14:17], v[142:145], v[208:211], v[14:17]
	v_mfma_f32_16x16x32_bf16 v[10:13], v[154:157], v[208:211], v[10:13]
	v_mfma_f32_16x16x32_bf16 v[62:65], v[146:149], v[182:185], v[62:65]
	v_mfma_f32_16x16x32_bf16 v[58:61], v[158:161], v[182:185], v[58:61]
	v_mfma_f32_16x16x32_bf16 v[46:49], v[146:149], v[190:193], v[46:49]
	v_mfma_f32_16x16x32_bf16 v[42:45], v[158:161], v[190:193], v[42:45]
	v_mfma_f32_16x16x32_bf16 v[30:33], v[146:149], v[198:201], v[30:33]
	v_mfma_f32_16x16x32_bf16 v[26:29], v[158:161], v[198:201], v[26:29]
	v_mfma_f32_16x16x32_bf16 v[14:17], v[146:149], v[212:215], v[14:17]
	v_mfma_f32_16x16x32_bf16 v[10:13], v[158:161], v[212:215], v[10:13]
	v_mfma_f32_16x16x32_bf16 v[54:57], v[162:165], v[178:181], v[54:57]
	v_mfma_f32_16x16x32_bf16 v[50:53], v[170:173], v[178:181], v[50:53]
	v_mfma_f32_16x16x32_bf16 v[38:41], v[162:165], v[186:189], v[38:41]
	v_mfma_f32_16x16x32_bf16 v[34:37], v[170:173], v[186:189], v[34:37]
	v_mfma_f32_16x16x32_bf16 v[22:25], v[162:165], v[194:197], v[22:25]
	v_mfma_f32_16x16x32_bf16 v[18:21], v[170:173], v[194:197], v[18:21]
	v_mfma_f32_16x16x32_bf16 v[6:9], v[162:165], v[208:211], v[6:9]
	v_mfma_f32_16x16x32_bf16 v[2:5], v[170:173], v[208:211], v[2:5]
	v_mfma_f32_16x16x32_bf16 v[54:57], v[166:169], v[182:185], v[54:57]
	v_mfma_f32_16x16x32_bf16 v[50:53], v[174:177], v[182:185], v[50:53]
	v_mfma_f32_16x16x32_bf16 v[38:41], v[166:169], v[190:193], v[38:41]
	v_mfma_f32_16x16x32_bf16 v[34:37], v[174:177], v[190:193], v[34:37]
	v_mfma_f32_16x16x32_bf16 v[22:25], v[166:169], v[198:201], v[22:25]
	v_mfma_f32_16x16x32_bf16 v[18:21], v[174:177], v[198:201], v[18:21]
	v_mfma_f32_16x16x32_bf16 v[6:9], v[166:169], v[212:215], v[6:9]
	v_mfma_f32_16x16x32_bf16 v[2:5], v[174:177], v[212:215], v[2:5]
	s_barrier
	s_setprio 0
	s_branch .Lpeel_mid_0
.LBB0_394:
	s_add_u32 s0, s24, 0xfff80080
	s_addc_u32 s1, s25, -1
	s_add_i32 s33, 0, 0x10000
	s_cmp_eq_u32 s60, 28
	s_cselect_b32 s29, s7, s1
	s_cselect_b32 s28, s19, s0
	s_cselect_b32 s27, s17, s59
	s_cselect_b32 s26, s49, s58
	s_add_i32 s55, 0, 0x14000
	ds_read_b128 v[142:145], v151
	ds_read_b128 v[146:149], v151 offset:1024
	ds_read_b128 v[154:157], v151 offset:2048
	ds_read_b128 v[158:161], v151 offset:3072
	ds_read_b128 v[162:165], v151 offset:16384
	ds_read_b128 v[166:169], v151 offset:17408
	ds_read_b128 v[170:173], v151 offset:18432
	ds_read_b128 v[174:177], v151 offset:19456
	s_add_i32 m0, s9, 0xc000
	ds_read_b128 v[178:181], v153
	ds_read_b128 v[182:185], v153 offset:1024
	ds_read_b128 v[186:189], v153 offset:2048
	ds_read_b128 v[190:193], v153 offset:3072
	ds_read_b128 v[194:197], v153 offset:4096
	ds_read_b128 v[198:201], v153 offset:5120
	ds_read_b128 v[208:211], v153 offset:6144
	ds_read_b128 v[212:215], v153 offset:7168
	global_load_lds_dwordx4 v138, s[24:25]
	s_add_i32 m0, s9, 0xe000
	s_nop 0
	global_load_lds_dwordx4 v140, s[24:25]
	s_waitcnt vmcnt(8)
	s_waitcnt lgkmcnt(0)
	s_setprio 1
	s_barrier
	v_mfma_f32_16x16x32_bf16 v[126:129], v[142:145], v[178:181], v[126:129]
	v_mfma_f32_16x16x32_bf16 v[122:125], v[154:157], v[178:181], v[122:125]
	v_mfma_f32_16x16x32_bf16 v[110:113], v[142:145], v[186:189], v[110:113]
	v_mfma_f32_16x16x32_bf16 v[106:109], v[154:157], v[186:189], v[106:109]
	v_mfma_f32_16x16x32_bf16 v[94:97], v[142:145], v[194:197], v[94:97]
	v_mfma_f32_16x16x32_bf16 v[90:93], v[154:157], v[194:197], v[90:93]
	v_mfma_f32_16x16x32_bf16 v[78:81], v[142:145], v[208:211], v[78:81]
	v_mfma_f32_16x16x32_bf16 v[74:77], v[154:157], v[208:211], v[74:77]
	v_mfma_f32_16x16x32_bf16 v[126:129], v[146:149], v[182:185], v[126:129]
	v_mfma_f32_16x16x32_bf16 v[122:125], v[158:161], v[182:185], v[122:125]
	v_mfma_f32_16x16x32_bf16 v[110:113], v[146:149], v[190:193], v[110:113]
	v_mfma_f32_16x16x32_bf16 v[106:109], v[158:161], v[190:193], v[106:109]
	v_mfma_f32_16x16x32_bf16 v[94:97], v[146:149], v[198:201], v[94:97]
	v_mfma_f32_16x16x32_bf16 v[90:93], v[158:161], v[198:201], v[90:93]
	v_mfma_f32_16x16x32_bf16 v[78:81], v[146:149], v[212:215], v[78:81]
	v_mfma_f32_16x16x32_bf16 v[74:77], v[158:161], v[212:215], v[74:77]
	v_mfma_f32_16x16x32_bf16 v[118:121], v[162:165], v[178:181], v[118:121]
	v_mfma_f32_16x16x32_bf16 v[114:117], v[170:173], v[178:181], v[114:117]
	v_mfma_f32_16x16x32_bf16 v[102:105], v[162:165], v[186:189], v[102:105]
	v_mfma_f32_16x16x32_bf16 v[98:101], v[170:173], v[186:189], v[98:101]
	v_mfma_f32_16x16x32_bf16 v[86:89], v[162:165], v[194:197], v[86:89]
	v_mfma_f32_16x16x32_bf16 v[82:85], v[170:173], v[194:197], v[82:85]
	v_mfma_f32_16x16x32_bf16 v[70:73], v[162:165], v[208:211], v[70:73]
	v_mfma_f32_16x16x32_bf16 v[66:69], v[170:173], v[208:211], v[66:69]
	v_mfma_f32_16x16x32_bf16 v[118:121], v[166:169], v[182:185], v[118:121]
	v_mfma_f32_16x16x32_bf16 v[114:117], v[174:177], v[182:185], v[114:117]
	v_mfma_f32_16x16x32_bf16 v[102:105], v[166:169], v[190:193], v[102:105]
	v_mfma_f32_16x16x32_bf16 v[98:101], v[174:177], v[190:193], v[98:101]
	v_mfma_f32_16x16x32_bf16 v[86:89], v[166:169], v[198:201], v[86:89]
	v_mfma_f32_16x16x32_bf16 v[82:85], v[174:177], v[198:201], v[82:85]
	v_mfma_f32_16x16x32_bf16 v[70:73], v[166:169], v[212:215], v[70:73]
	v_mfma_f32_16x16x32_bf16 v[66:69], v[174:177], v[212:215], v[66:69]
	s_barrier
	s_setprio 0
	s_add_i32 s0, s33, s34
	s_mov_b32 m0, s0
	ds_read_b128 v[178:181], v153 offset:16384
	ds_read_b128 v[182:185], v153 offset:17408
	ds_read_b128 v[186:189], v153 offset:18432
	ds_read_b128 v[190:193], v153 offset:19456
	ds_read_b128 v[194:197], v153 offset:20480
	ds_read_b128 v[198:201], v153 offset:21504
	ds_read_b128 v[208:211], v153 offset:22528
	ds_read_b128 v[212:215], v153 offset:23552
	global_load_lds_dwordx4 v132, s[26:27]
	s_add_i32 m0, s0, 0x2000
	s_add_u32 s0, s26, 0x80000
	s_addc_u32 s1, s27, 0
	s_add_i32 s33, s55, s34
	global_load_lds_dwordx4 v136, s[26:27]
	s_mov_b32 m0, s33
	s_nop 0
	global_load_lds_dwordx4 v132, s[0:1]
	s_add_i32 m0, s33, 0x2000
	s_nop 0
	global_load_lds_dwordx4 v136, s[0:1]
	s_mov_b32 m0, s9
	s_nop 0
	global_load_lds_dwordx4 v130, s[28:29]
	s_mov_b32 m0, s35
	s_nop 0
	global_load_lds_dwordx4 v134, s[28:29]
	s_waitcnt vmcnt(8)
	s_waitcnt lgkmcnt(0)
	s_setprio 1
	s_barrier
	v_mfma_f32_16x16x32_bf16 v[62:65], v[142:145], v[178:181], v[62:65]
	v_mfma_f32_16x16x32_bf16 v[58:61], v[154:157], v[178:181], v[58:61]
	v_mfma_f32_16x16x32_bf16 v[46:49], v[142:145], v[186:189], v[46:49]
	v_mfma_f32_16x16x32_bf16 v[42:45], v[154:157], v[186:189], v[42:45]
	v_mfma_f32_16x16x32_bf16 v[30:33], v[142:145], v[194:197], v[30:33]
	v_mfma_f32_16x16x32_bf16 v[26:29], v[154:157], v[194:197], v[26:29]
	v_mfma_f32_16x16x32_bf16 v[14:17], v[142:145], v[208:211], v[14:17]
	v_mfma_f32_16x16x32_bf16 v[10:13], v[154:157], v[208:211], v[10:13]
	v_mfma_f32_16x16x32_bf16 v[62:65], v[146:149], v[182:185], v[62:65]
	v_mfma_f32_16x16x32_bf16 v[58:61], v[158:161], v[182:185], v[58:61]
	v_mfma_f32_16x16x32_bf16 v[46:49], v[146:149], v[190:193], v[46:49]
	v_mfma_f32_16x16x32_bf16 v[42:45], v[158:161], v[190:193], v[42:45]
	v_mfma_f32_16x16x32_bf16 v[30:33], v[146:149], v[198:201], v[30:33]
	v_mfma_f32_16x16x32_bf16 v[26:29], v[158:161], v[198:201], v[26:29]
	v_mfma_f32_16x16x32_bf16 v[14:17], v[146:149], v[212:215], v[14:17]
	v_mfma_f32_16x16x32_bf16 v[10:13], v[158:161], v[212:215], v[10:13]
	v_mfma_f32_16x16x32_bf16 v[54:57], v[162:165], v[178:181], v[54:57]
	v_mfma_f32_16x16x32_bf16 v[50:53], v[170:173], v[178:181], v[50:53]
	v_mfma_f32_16x16x32_bf16 v[38:41], v[162:165], v[186:189], v[38:41]
	v_mfma_f32_16x16x32_bf16 v[34:37], v[170:173], v[186:189], v[34:37]
	v_mfma_f32_16x16x32_bf16 v[22:25], v[162:165], v[194:197], v[22:25]
	v_mfma_f32_16x16x32_bf16 v[18:21], v[170:173], v[194:197], v[18:21]
	v_mfma_f32_16x16x32_bf16 v[6:9], v[162:165], v[208:211], v[6:9]
	v_mfma_f32_16x16x32_bf16 v[2:5], v[170:173], v[208:211], v[2:5]
	v_mfma_f32_16x16x32_bf16 v[54:57], v[166:169], v[182:185], v[54:57]
	v_mfma_f32_16x16x32_bf16 v[50:53], v[174:177], v[182:185], v[50:53]
	v_mfma_f32_16x16x32_bf16 v[38:41], v[166:169], v[190:193], v[38:41]
	v_mfma_f32_16x16x32_bf16 v[34:37], v[174:177], v[190:193], v[34:37]
	v_mfma_f32_16x16x32_bf16 v[22:25], v[166:169], v[198:201], v[22:25]
	v_mfma_f32_16x16x32_bf16 v[18:21], v[174:177], v[198:201], v[18:21]
	v_mfma_f32_16x16x32_bf16 v[6:9], v[166:169], v[212:215], v[6:9]
	v_mfma_f32_16x16x32_bf16 v[2:5], v[174:177], v[212:215], v[2:5]
	s_barrier
	s_setprio 0
.Lpeel_mid_0:
	s_add_i32 s33, 0, 0x18000
	s_add_i32 s55, 0, 0x1c000
	ds_read_b128 v[142:145], v151 offset:32768
	ds_read_b128 v[146:149], v151 offset:33792
	ds_read_b128 v[154:157], v151 offset:34816
	ds_read_b128 v[158:161], v151 offset:35840
	ds_read_b128 v[162:165], v151 offset:49152
	ds_read_b128 v[166:169], v151 offset:50176
	ds_read_b128 v[170:173], v151 offset:51200
	ds_read_b128 v[174:177], v151 offset:52224
	s_add_u32 s0, s28, 0x80000
	s_addc_u32 s1, s29, 0
	s_mov_b32 m0, s36
	ds_read_b128 v[178:181], v153 offset:32768
	ds_read_b128 v[182:185], v153 offset:33792
	ds_read_b128 v[186:189], v153 offset:34816
	ds_read_b128 v[190:193], v153 offset:35840
	ds_read_b128 v[194:197], v153 offset:36864
	ds_read_b128 v[198:201], v153 offset:37888
	ds_read_b128 v[208:211], v153 offset:38912
	ds_read_b128 v[212:215], v153 offset:39936
	global_load_lds_dwordx4 v130, s[0:1]
	s_mov_b32 m0, s37
	s_nop 0
	global_load_lds_dwordx4 v134, s[0:1]
	s_waitcnt vmcnt(8)
	s_waitcnt lgkmcnt(0)
	s_setprio 1
	s_barrier
	v_mfma_f32_16x16x32_bf16 v[126:129], v[142:145], v[178:181], v[126:129]
	v_mfma_f32_16x16x32_bf16 v[122:125], v[154:157], v[178:181], v[122:125]
	v_mfma_f32_16x16x32_bf16 v[110:113], v[142:145], v[186:189], v[110:113]
	v_mfma_f32_16x16x32_bf16 v[106:109], v[154:157], v[186:189], v[106:109]
	v_mfma_f32_16x16x32_bf16 v[94:97], v[142:145], v[194:197], v[94:97]
	v_mfma_f32_16x16x32_bf16 v[90:93], v[154:157], v[194:197], v[90:93]
	v_mfma_f32_16x16x32_bf16 v[78:81], v[142:145], v[208:211], v[78:81]
	v_mfma_f32_16x16x32_bf16 v[74:77], v[154:157], v[208:211], v[74:77]
	v_mfma_f32_16x16x32_bf16 v[126:129], v[146:149], v[182:185], v[126:129]
	v_mfma_f32_16x16x32_bf16 v[122:125], v[158:161], v[182:185], v[122:125]
	v_mfma_f32_16x16x32_bf16 v[110:113], v[146:149], v[190:193], v[110:113]
	v_mfma_f32_16x16x32_bf16 v[106:109], v[158:161], v[190:193], v[106:109]
	v_mfma_f32_16x16x32_bf16 v[94:97], v[146:149], v[198:201], v[94:97]
	v_mfma_f32_16x16x32_bf16 v[90:93], v[158:161], v[198:201], v[90:93]
	v_mfma_f32_16x16x32_bf16 v[78:81], v[146:149], v[212:215], v[78:81]
	v_mfma_f32_16x16x32_bf16 v[74:77], v[158:161], v[212:215], v[74:77]
	v_mfma_f32_16x16x32_bf16 v[118:121], v[162:165], v[178:181], v[118:121]
	v_mfma_f32_16x16x32_bf16 v[114:117], v[170:173], v[178:181], v[114:117]
	v_mfma_f32_16x16x32_bf16 v[102:105], v[162:165], v[186:189], v[102:105]
	v_mfma_f32_16x16x32_bf16 v[98:101], v[170:173], v[186:189], v[98:101]
	v_mfma_f32_16x16x32_bf16 v[86:89], v[162:165], v[194:197], v[86:89]
	v_mfma_f32_16x16x32_bf16 v[82:85], v[170:173], v[194:197], v[82:85]
	v_mfma_f32_16x16x32_bf16 v[70:73], v[162:165], v[208:211], v[70:73]
	v_mfma_f32_16x16x32_bf16 v[66:69], v[170:173], v[208:211], v[66:69]
	v_mfma_f32_16x16x32_bf16 v[118:121], v[166:169], v[182:185], v[118:121]
	v_mfma_f32_16x16x32_bf16 v[114:117], v[174:177], v[182:185], v[114:117]
	v_mfma_f32_16x16x32_bf16 v[102:105], v[166:169], v[190:193], v[102:105]
	v_mfma_f32_16x16x32_bf16 v[98:101], v[174:177], v[190:193], v[98:101]
	v_mfma_f32_16x16x32_bf16 v[86:89], v[166:169], v[198:201], v[86:89]
	v_mfma_f32_16x16x32_bf16 v[82:85], v[174:177], v[198:201], v[82:85]
	v_mfma_f32_16x16x32_bf16 v[70:73], v[166:169], v[212:215], v[70:73]
	v_mfma_f32_16x16x32_bf16 v[66:69], v[174:177], v[212:215], v[66:69]
	s_barrier
	s_setprio 0
	s_add_i32 s0, s33, s34
	s_add_u32 s100, s26, 0x80
	s_addc_u32 s101, s27, 0
	s_mov_b32 m0, s0
	ds_read_b128 v[178:181], v153 offset:49152
	ds_read_b128 v[182:185], v153 offset:50176
	ds_read_b128 v[186:189], v153 offset:51200
	ds_read_b128 v[190:193], v153 offset:52224
	ds_read_b128 v[194:197], v153 offset:53248
	ds_read_b128 v[198:201], v153 offset:54272
	ds_read_b128 v[208:211], v153 offset:55296
	ds_read_b128 v[212:215], v153 offset:56320
	global_load_lds_dwordx4 v132, s[100:101]
	s_add_i32 m0, s0, 0x2000
	s_add_u32 s100, s26, 0x80
	s_addc_u32 s101, s27, 0
	s_add_u32 s0, s26, 0x80080
	s_addc_u32 s1, s27, 0
	s_add_i32 s26, s55, s34
	global_load_lds_dwordx4 v136, s[100:101]
	s_mov_b32 m0, s26
	s_nop 0
	global_load_lds_dwordx4 v132, s[0:1]
	s_add_i32 m0, s26, 0x2000
	s_nop 0
	global_load_lds_dwordx4 v136, s[0:1]
	s_add_u32 s100, s28, 0x80
	s_addc_u32 s101, s29, 0
	s_mov_b32 m0, s39
	s_nop 0
	global_load_lds_dwordx4 v130, s[100:101]
	s_add_u32 s100, s28, 0x80
	s_addc_u32 s101, s29, 0
	s_mov_b32 m0, s40
	s_nop 0
	global_load_lds_dwordx4 v134, s[100:101]
	s_waitcnt vmcnt(8)
	s_waitcnt lgkmcnt(0)
	s_setprio 1
	s_barrier
	v_mfma_f32_16x16x32_bf16 v[62:65], v[142:145], v[178:181], v[62:65]
	v_mfma_f32_16x16x32_bf16 v[58:61], v[154:157], v[178:181], v[58:61]
	v_mfma_f32_16x16x32_bf16 v[46:49], v[142:145], v[186:189], v[46:49]
	v_mfma_f32_16x16x32_bf16 v[42:45], v[154:157], v[186:189], v[42:45]
	v_mfma_f32_16x16x32_bf16 v[30:33], v[142:145], v[194:197], v[30:33]
	v_mfma_f32_16x16x32_bf16 v[26:29], v[154:157], v[194:197], v[26:29]
	v_mfma_f32_16x16x32_bf16 v[14:17], v[142:145], v[208:211], v[14:17]
	v_mfma_f32_16x16x32_bf16 v[10:13], v[154:157], v[208:211], v[10:13]
	v_mfma_f32_16x16x32_bf16 v[62:65], v[146:149], v[182:185], v[62:65]
	v_mfma_f32_16x16x32_bf16 v[58:61], v[158:161], v[182:185], v[58:61]
	v_mfma_f32_16x16x32_bf16 v[46:49], v[146:149], v[190:193], v[46:49]
	v_mfma_f32_16x16x32_bf16 v[42:45], v[158:161], v[190:193], v[42:45]
	v_mfma_f32_16x16x32_bf16 v[30:33], v[146:149], v[198:201], v[30:33]
	v_mfma_f32_16x16x32_bf16 v[26:29], v[158:161], v[198:201], v[26:29]
	v_mfma_f32_16x16x32_bf16 v[14:17], v[146:149], v[212:215], v[14:17]
	v_mfma_f32_16x16x32_bf16 v[10:13], v[158:161], v[212:215], v[10:13]
	v_mfma_f32_16x16x32_bf16 v[54:57], v[162:165], v[178:181], v[54:57]
	v_mfma_f32_16x16x32_bf16 v[50:53], v[170:173], v[178:181], v[50:53]
	v_mfma_f32_16x16x32_bf16 v[38:41], v[162:165], v[186:189], v[38:41]
	v_mfma_f32_16x16x32_bf16 v[34:37], v[170:173], v[186:189], v[34:37]
	v_mfma_f32_16x16x32_bf16 v[22:25], v[162:165], v[194:197], v[22:25]
	v_mfma_f32_16x16x32_bf16 v[18:21], v[170:173], v[194:197], v[18:21]
	v_mfma_f32_16x16x32_bf16 v[6:9], v[162:165], v[208:211], v[6:9]
	v_mfma_f32_16x16x32_bf16 v[2:5], v[170:173], v[208:211], v[2:5]
	v_mfma_f32_16x16x32_bf16 v[54:57], v[166:169], v[182:185], v[54:57]
	v_mfma_f32_16x16x32_bf16 v[50:53], v[174:177], v[182:185], v[50:53]
	v_mfma_f32_16x16x32_bf16 v[38:41], v[166:169], v[190:193], v[38:41]
	v_mfma_f32_16x16x32_bf16 v[34:37], v[174:177], v[190:193], v[34:37]
	v_mfma_f32_16x16x32_bf16 v[22:25], v[166:169], v[198:201], v[22:25]
	v_mfma_f32_16x16x32_bf16 v[18:21], v[174:177], v[198:201], v[18:21]
	v_mfma_f32_16x16x32_bf16 v[6:9], v[166:169], v[212:215], v[6:9]
	v_mfma_f32_16x16x32_bf16 v[2:5], v[174:177], v[212:215], v[2:5]
	s_barrier
	s_setprio 0
	s_add_i32 s60, s60, 2
	s_add_u32 s24, s24, 0x100
	s_addc_u32 s25, s25, 0
	s_add_u32 s58, s58, 0x100
	s_addc_u32 s59, s59, 0
	s_cmp_gt_u32 s60, 29
	s_cbranch_scc0 .LBB0_394
	s_mov_b32 s101, 0x80000001
	s_and_b64 vcc, exec, s[14:15]
	s_cbranch_vccz .LBB0_397
	s_barrier

.LBB0_831:
	v_lshrrev_b32_e32 v18, 1, v8
	v_and_b32_e32 v18, 24, v18
	s_lshl_b32 s0, s0, 5
	v_and_b32_e32 v9, 15, v8
	v_lshlrev_b32_e32 v19, 1, v18
	v_lshlrev_b32_e32 v8, 2, v8
	s_and_b32 s3, s0, 0x60
	v_lshl_add_u64 v[10:11], s[20:21], 0, v[202:203]
	v_mov_b32_e32 v131, v203
	v_readlane_b32 s18, v254, 3
	v_lshl_or_b32 v142, s1, 6, v9
	v_lshl_or_b32 v9, v9, 6, v19
	s_lshl_b32 s1, s1, 13
	v_and_b32_e32 v8, 32, v8
	s_lshl_b32 s0, s3, 7
	v_lshl_add_u64 v[12:13], s[20:21], 0, v[130:131]
	v_mov_b32_e32 v135, v203
	v_readlane_b32 s19, v254, 4
	v_bitop3_b32 v19, v9, s1, v8 bitop3:0xde
	v_bitop3_b32 v143, v9, s0, v8 bitop3:0xde
	v_add_u32_e32 v143, 0x10000, v143
	s_add_i32 m0, s27, 0x18000
	v_lshl_add_u64 v[8:9], v[10:11], 0, s[80:81]
	v_lshl_add_u64 v[14:15], s[18:19], 0, v[134:135]
	v_mov_b32_e32 v133, v203
	s_waitcnt vmcnt(2)
	s_barrier
	global_load_lds_dwordx4 v[8:9], off
	v_lshl_add_u64 v[8:9], v[12:13], 0, s[80:81]
	s_add_i32 m0, s27, 0x1a000
	s_add_i32 s31, s27, 0x8000
	s_add_i32 s34, s27, 0xa000
	v_lshl_add_u64 v[16:17], s[18:19], 0, v[132:133]
	global_load_lds_dwordx4 v[8:9], off
	v_lshl_add_u64 v[8:9], v[14:15], 0, s[80:81]
	s_mov_b32 m0, s31
	s_add_u32 s0, s20, 0x80080
	global_load_lds_dwordx4 v[8:9], off
	v_lshl_add_u64 v[8:9], v[16:17], 0, s[80:81]
	s_mov_b32 m0, s34
	s_addc_u32 s1, s21, 0
	global_load_lds_dwordx4 v[8:9], off
	s_add_i32 m0, s27, 0x1c000
	v_lshl_add_u64 v[8:9], s[0:1], 0, v[202:203]
	global_load_lds_dwordx4 v[8:9], off
	v_lshl_add_u64 v[8:9], s[0:1], 0, v[130:131]
	s_add_i32 m0, s27, 0x1e000
	s_cmpk_lt_u32 s2, 0x100
	global_load_lds_dwordx4 v[8:9], off
	v_lshlrev_b32_e32 v8, 15, v6
	v_and_b32_e32 v8, 0xffff0000, v8
	v_lshl_add_u32 v5, v5, 12, v8
	v_and_b32_e32 v6, 1, v6
	v_lshl_or_b32 v5, v6, 6, v5
	v_lshl_add_u32 v136, v7, 1, v5
	v_lshlrev_b32_e32 v5, 15, v2
	v_and_b32_e32 v5, 0xffff0000, v5
	s_waitcnt vmcnt(6)
	v_lshl_add_u32 v3, v3, 12, v5
	v_and_b32_e32 v2, 1, v2
	v_lshl_or_b32 v2, v2, 6, v3
	v_readlane_b32 s0, v254, 1
	s_cselect_b64 s[6:7], -1, 0
	v_or_b32_e32 v144, s3, v18
	v_mov_b32_e32 v137, v203
	v_lshl_add_u32 v138, v4, 1, v2
	v_mov_b32_e32 v139, v203
	s_mov_b32 s35, 0
	v_add_u32_e32 v145, 0, v19
	v_readlane_b32 s36, v254, 13
	s_mov_b32 s37, s0
	s_barrier
	v_readlane_b32 s1, v254, 2
	s_waitcnt vmcnt(0)
	s_mov_b32 s101, 0
	s_branch .LBB0_834

.LBB0_836:
	s_ashr_i32 s11, s10, 31
	s_lshl_b64 s[0:1], s[10:11], 20
	s_add_u32 s14, s42, s0
	s_addc_u32 s15, s43, s1
	s_and_b64 s[0:1], s[2:3], exec
	s_cselect_b32 s11, s15, s19
	s_cselect_b32 s38, s14, s18
	s_ashr_i32 s9, s8, 31
	s_lshl_b64 s[0:1], s[8:9], 20
	s_add_u32 s16, s24, s0
	s_addc_u32 s17, s25, s1
	s_and_b64 s[0:1], s[2:3], exec
	s_cselect_b32 s9, s17, s21
	s_cselect_b32 s39, s16, s20
	s_add_u32 s18, s18, 0x80080
	s_addc_u32 s19, s19, 0
	s_add_u32 s49, s20, 0x100
	v_mov_b32_e32 v2, 0
	s_addc_u32 s58, s21, 0
	s_mov_b32 s59, -2
	v_mov_b32_e32 v3, v2
	v_pk_mov_b32 v[4:5], v[2:3], v[2:3] op_sel:[0,1]
	v_pk_mov_b32 v[10:11], v[2:3], v[2:3] op_sel:[0,1]
	v_pk_mov_b32 v[12:13], v[2:3], v[2:3] op_sel:[0,1]
	v_pk_mov_b32 v[18:19], v[2:3], v[2:3] op_sel:[0,1]
	v_pk_mov_b32 v[20:21], v[2:3], v[2:3] op_sel:[0,1]
	v_pk_mov_b32 v[26:27], v[2:3], v[2:3] op_sel:[0,1]
	v_pk_mov_b32 v[28:29], v[2:3], v[2:3] op_sel:[0,1]
	v_pk_mov_b32 v[34:35], v[2:3], v[2:3] op_sel:[0,1]
	v_pk_mov_b32 v[36:37], v[2:3], v[2:3] op_sel:[0,1]
	v_pk_mov_b32 v[42:43], v[2:3], v[2:3] op_sel:[0,1]
	v_pk_mov_b32 v[44:45], v[2:3], v[2:3] op_sel:[0,1]
	v_pk_mov_b32 v[50:51], v[2:3], v[2:3] op_sel:[0,1]
	v_pk_mov_b32 v[52:53], v[2:3], v[2:3] op_sel:[0,1]
	v_pk_mov_b32 v[58:59], v[2:3], v[2:3] op_sel:[0,1]
	v_pk_mov_b32 v[60:61], v[2:3], v[2:3] op_sel:[0,1]
	v_pk_mov_b32 v[6:7], v[2:3], v[2:3] op_sel:[0,1]
	v_pk_mov_b32 v[8:9], v[2:3], v[2:3] op_sel:[0,1]
	v_pk_mov_b32 v[14:15], v[2:3], v[2:3] op_sel:[0,1]
	v_pk_mov_b32 v[16:17], v[2:3], v[2:3] op_sel:[0,1]
	v_pk_mov_b32 v[22:23], v[2:3], v[2:3] op_sel:[0,1]
	v_pk_mov_b32 v[24:25], v[2:3], v[2:3] op_sel:[0,1]
	v_pk_mov_b32 v[30:31], v[2:3], v[2:3] op_sel:[0,1]
	v_pk_mov_b32 v[32:33], v[2:3], v[2:3] op_sel:[0,1]
	v_pk_mov_b32 v[38:39], v[2:3], v[2:3] op_sel:[0,1]
	v_pk_mov_b32 v[40:41], v[2:3], v[2:3] op_sel:[0,1]
	v_pk_mov_b32 v[46:47], v[2:3], v[2:3] op_sel:[0,1]
	v_pk_mov_b32 v[48:49], v[2:3], v[2:3] op_sel:[0,1]
	v_pk_mov_b32 v[54:55], v[2:3], v[2:3] op_sel:[0,1]
	v_pk_mov_b32 v[56:57], v[2:3], v[2:3] op_sel:[0,1]
	v_pk_mov_b32 v[62:63], v[2:3], v[2:3] op_sel:[0,1]
	v_pk_mov_b32 v[64:65], v[2:3], v[2:3] op_sel:[0,1]
	v_pk_mov_b32 v[66:67], v[2:3], v[2:3] op_sel:[0,1]
	v_pk_mov_b32 v[68:69], v[2:3], v[2:3] op_sel:[0,1]
	v_pk_mov_b32 v[74:75], v[2:3], v[2:3] op_sel:[0,1]
	v_pk_mov_b32 v[76:77], v[2:3], v[2:3] op_sel:[0,1]
	v_pk_mov_b32 v[82:83], v[2:3], v[2:3] op_sel:[0,1]
	v_pk_mov_b32 v[84:85], v[2:3], v[2:3] op_sel:[0,1]
	v_pk_mov_b32 v[90:91], v[2:3], v[2:3] op_sel:[0,1]
	v_pk_mov_b32 v[92:93], v[2:3], v[2:3] op_sel:[0,1]
	v_pk_mov_b32 v[98:99], v[2:3], v[2:3] op_sel:[0,1]
	v_pk_mov_b32 v[100:101], v[2:3], v[2:3] op_sel:[0,1]
	v_pk_mov_b32 v[106:107], v[2:3], v[2:3] op_sel:[0,1]
	v_pk_mov_b32 v[108:109], v[2:3], v[2:3] op_sel:[0,1]
	v_pk_mov_b32 v[114:115], v[2:3], v[2:3] op_sel:[0,1]
	v_pk_mov_b32 v[116:117], v[2:3], v[2:3] op_sel:[0,1]
	v_pk_mov_b32 v[122:123], v[2:3], v[2:3] op_sel:[0,1]
	v_pk_mov_b32 v[124:125], v[2:3], v[2:3] op_sel:[0,1]
	v_pk_mov_b32 v[70:71], v[2:3], v[2:3] op_sel:[0,1]
	v_pk_mov_b32 v[72:73], v[2:3], v[2:3] op_sel:[0,1]
	v_pk_mov_b32 v[78:79], v[2:3], v[2:3] op_sel:[0,1]
	v_pk_mov_b32 v[80:81], v[2:3], v[2:3] op_sel:[0,1]
	v_pk_mov_b32 v[86:87], v[2:3], v[2:3] op_sel:[0,1]
	v_pk_mov_b32 v[88:89], v[2:3], v[2:3] op_sel:[0,1]
	v_pk_mov_b32 v[94:95], v[2:3], v[2:3] op_sel:[0,1]
	v_pk_mov_b32 v[96:97], v[2:3], v[2:3] op_sel:[0,1]
	v_pk_mov_b32 v[102:103], v[2:3], v[2:3] op_sel:[0,1]
	v_pk_mov_b32 v[104:105], v[2:3], v[2:3] op_sel:[0,1]
	v_pk_mov_b32 v[110:111], v[2:3], v[2:3] op_sel:[0,1]
	v_pk_mov_b32 v[112:113], v[2:3], v[2:3] op_sel:[0,1]
	v_pk_mov_b32 v[118:119], v[2:3], v[2:3] op_sel:[0,1]
	v_pk_mov_b32 v[120:121], v[2:3], v[2:3] op_sel:[0,1]
	v_pk_mov_b32 v[126:127], v[2:3], v[2:3] op_sel:[0,1]
	v_pk_mov_b32 v[128:129], v[2:3], v[2:3] op_sel:[0,1]
	s_cmp_eq_u32 s101, 0x80000001
	s_cbranch_scc0 .LBB0_837
	s_add_u32 s0, s18, 0xfff80080
	s_addc_u32 s1, s19, -1
	s_add_i32 s33, 0, 0x10000
	s_cmp_eq_u32 s59, 28
	s_cselect_b32 s23, s11, s1
	s_cselect_b32 s22, s38, s0
	s_cselect_b32 s21, s9, s58
	s_cselect_b32 s20, s39, s49
	s_add_i32 s55, 0, 0x14000
	ds_read_b128 v[146:149], v143
	ds_read_b128 v[150:153], v143 offset:1024
	ds_read_b128 v[154:157], v143 offset:2048
	ds_read_b128 v[158:161], v143 offset:3072
	ds_read_b128 v[162:165], v143 offset:16384
	ds_read_b128 v[166:169], v143 offset:17408
	ds_read_b128 v[170:173], v143 offset:18432
	ds_read_b128 v[174:177], v143 offset:19456
	s_add_i32 m0, s27, 0xc000
	ds_read_b128 v[178:181], v145
	ds_read_b128 v[182:185], v145 offset:1024
	ds_read_b128 v[186:189], v145 offset:2048
	ds_read_b128 v[190:193], v145 offset:3072
	ds_read_b128 v[194:197], v145 offset:4096
	ds_read_b128 v[198:201], v145 offset:5120
	ds_read_b128 v[208:211], v145 offset:6144
	ds_read_b128 v[212:215], v145 offset:7168
	global_load_lds_dwordx4 v136, s[18:19]
	s_add_i32 m0, s27, 0xe000
	s_nop 0
	global_load_lds_dwordx4 v138, s[18:19]
	s_waitcnt vmcnt(16)
	s_waitcnt lgkmcnt(0)
	s_setprio 1
	s_barrier
	v_mfma_f32_16x16x32_bf16 v[126:129], v[146:149], v[178:181], v[126:129]
	v_mfma_f32_16x16x32_bf16 v[118:121], v[154:157], v[178:181], v[118:121]
	v_mfma_f32_16x16x32_bf16 v[110:113], v[146:149], v[186:189], v[110:113]
	v_mfma_f32_16x16x32_bf16 v[102:105], v[154:157], v[186:189], v[102:105]
	v_mfma_f32_16x16x32_bf16 v[94:97], v[146:149], v[194:197], v[94:97]
	v_mfma_f32_16x16x32_bf16 v[86:89], v[154:157], v[194:197], v[86:89]
	v_mfma_f32_16x16x32_bf16 v[78:81], v[146:149], v[208:211], v[78:81]
	v_mfma_f32_16x16x32_bf16 v[70:73], v[154:157], v[208:211], v[70:73]
	v_mfma_f32_16x16x32_bf16 v[126:129], v[150:153], v[182:185], v[126:129]
	v_mfma_f32_16x16x32_bf16 v[118:121], v[158:161], v[182:185], v[118:121]
	v_mfma_f32_16x16x32_bf16 v[110:113], v[150:153], v[190:193], v[110:113]
	v_mfma_f32_16x16x32_bf16 v[102:105], v[158:161], v[190:193], v[102:105]
	v_mfma_f32_16x16x32_bf16 v[94:97], v[150:153], v[198:201], v[94:97]
	v_mfma_f32_16x16x32_bf16 v[86:89], v[158:161], v[198:201], v[86:89]
	v_mfma_f32_16x16x32_bf16 v[78:81], v[150:153], v[212:215], v[78:81]
	v_mfma_f32_16x16x32_bf16 v[70:73], v[158:161], v[212:215], v[70:73]
	v_mfma_f32_16x16x32_bf16 v[122:125], v[162:165], v[178:181], v[122:125]
	v_mfma_f32_16x16x32_bf16 v[114:117], v[170:173], v[178:181], v[114:117]
	v_mfma_f32_16x16x32_bf16 v[106:109], v[162:165], v[186:189], v[106:109]
	v_mfma_f32_16x16x32_bf16 v[98:101], v[170:173], v[186:189], v[98:101]
	v_mfma_f32_16x16x32_bf16 v[90:93], v[162:165], v[194:197], v[90:93]
	v_mfma_f32_16x16x32_bf16 v[82:85], v[170:173], v[194:197], v[82:85]
	v_mfma_f32_16x16x32_bf16 v[74:77], v[162:165], v[208:211], v[74:77]
	v_mfma_f32_16x16x32_bf16 v[66:69], v[170:173], v[208:211], v[66:69]
	v_mfma_f32_16x16x32_bf16 v[122:125], v[166:169], v[182:185], v[122:125]
	v_mfma_f32_16x16x32_bf16 v[114:117], v[174:177], v[182:185], v[114:117]
	v_mfma_f32_16x16x32_bf16 v[106:109], v[166:169], v[190:193], v[106:109]
	v_mfma_f32_16x16x32_bf16 v[98:101], v[174:177], v[190:193], v[98:101]
	v_mfma_f32_16x16x32_bf16 v[90:93], v[166:169], v[198:201], v[90:93]
	v_mfma_f32_16x16x32_bf16 v[82:85], v[174:177], v[198:201], v[82:85]
	v_mfma_f32_16x16x32_bf16 v[74:77], v[166:169], v[212:215], v[74:77]
	v_mfma_f32_16x16x32_bf16 v[66:69], v[174:177], v[212:215], v[66:69]
	s_barrier
	s_setprio 0
	s_add_i32 s0, s33, s26
	s_mov_b32 m0, s0
	ds_read_b128 v[178:181], v145 offset:16384
	ds_read_b128 v[182:185], v145 offset:17408
	ds_read_b128 v[186:189], v145 offset:18432
	ds_read_b128 v[190:193], v145 offset:19456
	ds_read_b128 v[194:197], v145 offset:20480
	ds_read_b128 v[198:201], v145 offset:21504
	ds_read_b128 v[208:211], v145 offset:22528
	ds_read_b128 v[212:215], v145 offset:23552
	global_load_lds_dwordx4 v202, s[20:21]
	s_add_i32 m0, s0, 0x2000
	s_add_u32 s0, s20, 0x80000
	s_addc_u32 s1, s21, 0
	s_add_i32 s33, s55, s26
	global_load_lds_dwordx4 v130, s[20:21]
	s_mov_b32 m0, s33
	s_nop 0
	global_load_lds_dwordx4 v202, s[0:1]
	s_add_i32 m0, s33, 0x2000
	s_nop 0
	global_load_lds_dwordx4 v130, s[0:1]
	s_mov_b32 m0, s27
	s_nop 0
	global_load_lds_dwordx4 v134, s[22:23]
	s_mov_b32 m0, s28
	s_nop 0
	global_load_lds_dwordx4 v132, s[22:23]
	s_waitcnt vmcnt(16)
	s_waitcnt lgkmcnt(0)
	s_setprio 1
	s_barrier
	v_mfma_f32_16x16x32_bf16 v[62:65], v[146:149], v[178:181], v[62:65]
	v_mfma_f32_16x16x32_bf16 v[54:57], v[154:157], v[178:181], v[54:57]
	v_mfma_f32_16x16x32_bf16 v[46:49], v[146:149], v[186:189], v[46:49]
	v_mfma_f32_16x16x32_bf16 v[38:41], v[154:157], v[186:189], v[38:41]
	v_mfma_f32_16x16x32_bf16 v[30:33], v[146:149], v[194:197], v[30:33]
	v_mfma_f32_16x16x32_bf16 v[22:25], v[154:157], v[194:197], v[22:25]
	v_mfma_f32_16x16x32_bf16 v[14:17], v[146:149], v[208:211], v[14:17]
	v_mfma_f32_16x16x32_bf16 v[6:9], v[154:157], v[208:211], v[6:9]
	v_mfma_f32_16x16x32_bf16 v[62:65], v[150:153], v[182:185], v[62:65]
	v_mfma_f32_16x16x32_bf16 v[54:57], v[158:161], v[182:185], v[54:57]
	v_mfma_f32_16x16x32_bf16 v[46:49], v[150:153], v[190:193], v[46:49]
	v_mfma_f32_16x16x32_bf16 v[38:41], v[158:161], v[190:193], v[38:41]
	v_mfma_f32_16x16x32_bf16 v[30:33], v[150:153], v[198:201], v[30:33]
	v_mfma_f32_16x16x32_bf16 v[22:25], v[158:161], v[198:201], v[22:25]
	v_mfma_f32_16x16x32_bf16 v[14:17], v[150:153], v[212:215], v[14:17]
	v_mfma_f32_16x16x32_bf16 v[6:9], v[158:161], v[212:215], v[6:9]
	v_mfma_f32_16x16x32_bf16 v[58:61], v[162:165], v[178:181], v[58:61]
	v_mfma_f32_16x16x32_bf16 v[50:53], v[170:173], v[178:181], v[50:53]
	v_mfma_f32_16x16x32_bf16 v[42:45], v[162:165], v[186:189], v[42:45]
	v_mfma_f32_16x16x32_bf16 v[34:37], v[170:173], v[186:189], v[34:37]
	v_mfma_f32_16x16x32_bf16 v[26:29], v[162:165], v[194:197], v[26:29]
	v_mfma_f32_16x16x32_bf16 v[18:21], v[170:173], v[194:197], v[18:21]
	v_mfma_f32_16x16x32_bf16 v[10:13], v[162:165], v[208:211], v[10:13]
	v_mfma_f32_16x16x32_bf16 v[2:5], v[170:173], v[208:211], v[2:5]
	v_mfma_f32_16x16x32_bf16 v[58:61], v[166:169], v[182:185], v[58:61]
	v_mfma_f32_16x16x32_bf16 v[50:53], v[174:177], v[182:185], v[50:53]
	v_mfma_f32_16x16x32_bf16 v[42:45], v[166:169], v[190:193], v[42:45]
	v_mfma_f32_16x16x32_bf16 v[34:37], v[174:177], v[190:193], v[34:37]
	v_mfma_f32_16x16x32_bf16 v[26:29], v[166:169], v[198:201], v[26:29]
	v_mfma_f32_16x16x32_bf16 v[18:21], v[174:177], v[198:201], v[18:21]
	v_mfma_f32_16x16x32_bf16 v[10:13], v[166:169], v[212:215], v[10:13]
	v_mfma_f32_16x16x32_bf16 v[2:5], v[174:177], v[212:215], v[2:5]
	s_barrier
	s_setprio 0
	s_branch .Lpeel_mid_3
.LBB0_837:
	s_add_u32 s0, s18, 0xfff80080
	s_addc_u32 s1, s19, -1
	s_add_i32 s33, 0, 0x10000
	s_cmp_eq_u32 s59, 28
	s_cselect_b32 s23, s11, s1
	s_cselect_b32 s22, s38, s0
	s_cselect_b32 s21, s9, s58
	s_cselect_b32 s20, s39, s49
	s_add_i32 s55, 0, 0x14000
	ds_read_b128 v[146:149], v143
	ds_read_b128 v[150:153], v143 offset:1024
	ds_read_b128 v[154:157], v143 offset:2048
	ds_read_b128 v[158:161], v143 offset:3072
	ds_read_b128 v[162:165], v143 offset:16384
	ds_read_b128 v[166:169], v143 offset:17408
	ds_read_b128 v[170:173], v143 offset:18432
	ds_read_b128 v[174:177], v143 offset:19456
	s_add_i32 m0, s27, 0xc000
	ds_read_b128 v[178:181], v145
	ds_read_b128 v[182:185], v145 offset:1024
	ds_read_b128 v[186:189], v145 offset:2048
	ds_read_b128 v[190:193], v145 offset:3072
	ds_read_b128 v[194:197], v145 offset:4096
	ds_read_b128 v[198:201], v145 offset:5120
	ds_read_b128 v[208:211], v145 offset:6144
	ds_read_b128 v[212:215], v145 offset:7168
	global_load_lds_dwordx4 v136, s[18:19]
	s_add_i32 m0, s27, 0xe000
	s_nop 0
	global_load_lds_dwordx4 v138, s[18:19]
	s_waitcnt vmcnt(8)
	s_waitcnt lgkmcnt(0)
	s_setprio 1
	s_barrier
	v_mfma_f32_16x16x32_bf16 v[126:129], v[146:149], v[178:181], v[126:129]
	v_mfma_f32_16x16x32_bf16 v[118:121], v[154:157], v[178:181], v[118:121]
	v_mfma_f32_16x16x32_bf16 v[110:113], v[146:149], v[186:189], v[110:113]
	v_mfma_f32_16x16x32_bf16 v[102:105], v[154:157], v[186:189], v[102:105]
	v_mfma_f32_16x16x32_bf16 v[94:97], v[146:149], v[194:197], v[94:97]
	v_mfma_f32_16x16x32_bf16 v[86:89], v[154:157], v[194:197], v[86:89]
	v_mfma_f32_16x16x32_bf16 v[78:81], v[146:149], v[208:211], v[78:81]
	v_mfma_f32_16x16x32_bf16 v[70:73], v[154:157], v[208:211], v[70:73]
	v_mfma_f32_16x16x32_bf16 v[126:129], v[150:153], v[182:185], v[126:129]
	v_mfma_f32_16x16x32_bf16 v[118:121], v[158:161], v[182:185], v[118:121]
	v_mfma_f32_16x16x32_bf16 v[110:113], v[150:153], v[190:193], v[110:113]
	v_mfma_f32_16x16x32_bf16 v[102:105], v[158:161], v[190:193], v[102:105]
	v_mfma_f32_16x16x32_bf16 v[94:97], v[150:153], v[198:201], v[94:97]
	v_mfma_f32_16x16x32_bf16 v[86:89], v[158:161], v[198:201], v[86:89]
	v_mfma_f32_16x16x32_bf16 v[78:81], v[150:153], v[212:215], v[78:81]
	v_mfma_f32_16x16x32_bf16 v[70:73], v[158:161], v[212:215], v[70:73]
	v_mfma_f32_16x16x32_bf16 v[122:125], v[162:165], v[178:181], v[122:125]
	v_mfma_f32_16x16x32_bf16 v[114:117], v[170:173], v[178:181], v[114:117]
	v_mfma_f32_16x16x32_bf16 v[106:109], v[162:165], v[186:189], v[106:109]
	v_mfma_f32_16x16x32_bf16 v[98:101], v[170:173], v[186:189], v[98:101]
	v_mfma_f32_16x16x32_bf16 v[90:93], v[162:165], v[194:197], v[90:93]
	v_mfma_f32_16x16x32_bf16 v[82:85], v[170:173], v[194:197], v[82:85]
	v_mfma_f32_16x16x32_bf16 v[74:77], v[162:165], v[208:211], v[74:77]
	v_mfma_f32_16x16x32_bf16 v[66:69], v[170:173], v[208:211], v[66:69]
	v_mfma_f32_16x16x32_bf16 v[122:125], v[166:169], v[182:185], v[122:125]
	v_mfma_f32_16x16x32_bf16 v[114:117], v[174:177], v[182:185], v[114:117]
	v_mfma_f32_16x16x32_bf16 v[106:109], v[166:169], v[190:193], v[106:109]
	v_mfma_f32_16x16x32_bf16 v[98:101], v[174:177], v[190:193], v[98:101]
	v_mfma_f32_16x16x32_bf16 v[90:93], v[166:169], v[198:201], v[90:93]
	v_mfma_f32_16x16x32_bf16 v[82:85], v[174:177], v[198:201], v[82:85]
	v_mfma_f32_16x16x32_bf16 v[74:77], v[166:169], v[212:215], v[74:77]
	v_mfma_f32_16x16x32_bf16 v[66:69], v[174:177], v[212:215], v[66:69]
	s_barrier
	s_setprio 0
	s_add_i32 s0, s33, s26
	s_mov_b32 m0, s0
	ds_read_b128 v[178:181], v145 offset:16384
	ds_read_b128 v[182:185], v145 offset:17408
	ds_read_b128 v[186:189], v145 offset:18432
	ds_read_b128 v[190:193], v145 offset:19456
	ds_read_b128 v[194:197], v145 offset:20480
	ds_read_b128 v[198:201], v145 offset:21504
	ds_read_b128 v[208:211], v145 offset:22528
	ds_read_b128 v[212:215], v145 offset:23552
	global_load_lds_dwordx4 v202, s[20:21]
	s_add_i32 m0, s0, 0x2000
	s_add_u32 s0, s20, 0x80000
	s_addc_u32 s1, s21, 0
	s_add_i32 s33, s55, s26
	global_load_lds_dwordx4 v130, s[20:21]
	s_mov_b32 m0, s33
	s_nop 0
	global_load_lds_dwordx4 v202, s[0:1]
	s_add_i32 m0, s33, 0x2000
	s_nop 0
	global_load_lds_dwordx4 v130, s[0:1]
	s_mov_b32 m0, s27
	s_nop 0
	global_load_lds_dwordx4 v134, s[22:23]
	s_mov_b32 m0, s28
	s_nop 0
	global_load_lds_dwordx4 v132, s[22:23]
	s_waitcnt vmcnt(8)
	s_waitcnt lgkmcnt(0)
	s_setprio 1
	s_barrier
	v_mfma_f32_16x16x32_bf16 v[62:65], v[146:149], v[178:181], v[62:65]
	v_mfma_f32_16x16x32_bf16 v[54:57], v[154:157], v[178:181], v[54:57]
	v_mfma_f32_16x16x32_bf16 v[46:49], v[146:149], v[186:189], v[46:49]
	v_mfma_f32_16x16x32_bf16 v[38:41], v[154:157], v[186:189], v[38:41]
	v_mfma_f32_16x16x32_bf16 v[30:33], v[146:149], v[194:197], v[30:33]
	v_mfma_f32_16x16x32_bf16 v[22:25], v[154:157], v[194:197], v[22:25]
	v_mfma_f32_16x16x32_bf16 v[14:17], v[146:149], v[208:211], v[14:17]
	v_mfma_f32_16x16x32_bf16 v[6:9], v[154:157], v[208:211], v[6:9]
	v_mfma_f32_16x16x32_bf16 v[62:65], v[150:153], v[182:185], v[62:65]
	v_mfma_f32_16x16x32_bf16 v[54:57], v[158:161], v[182:185], v[54:57]
	v_mfma_f32_16x16x32_bf16 v[46:49], v[150:153], v[190:193], v[46:49]
	v_mfma_f32_16x16x32_bf16 v[38:41], v[158:161], v[190:193], v[38:41]
	v_mfma_f32_16x16x32_bf16 v[30:33], v[150:153], v[198:201], v[30:33]
	v_mfma_f32_16x16x32_bf16 v[22:25], v[158:161], v[198:201], v[22:25]
	v_mfma_f32_16x16x32_bf16 v[14:17], v[150:153], v[212:215], v[14:17]
	v_mfma_f32_16x16x32_bf16 v[6:9], v[158:161], v[212:215], v[6:9]
	v_mfma_f32_16x16x32_bf16 v[58:61], v[162:165], v[178:181], v[58:61]
	v_mfma_f32_16x16x32_bf16 v[50:53], v[170:173], v[178:181], v[50:53]
	v_mfma_f32_16x16x32_bf16 v[42:45], v[162:165], v[186:189], v[42:45]
	v_mfma_f32_16x16x32_bf16 v[34:37], v[170:173], v[186:189], v[34:37]
	v_mfma_f32_16x16x32_bf16 v[26:29], v[162:165], v[194:197], v[26:29]
	v_mfma_f32_16x16x32_bf16 v[18:21], v[170:173], v[194:197], v[18:21]
	v_mfma_f32_16x16x32_bf16 v[10:13], v[162:165], v[208:211], v[10:13]
	v_mfma_f32_16x16x32_bf16 v[2:5], v[170:173], v[208:211], v[2:5]
	v_mfma_f32_16x16x32_bf16 v[58:61], v[166:169], v[182:185], v[58:61]
	v_mfma_f32_16x16x32_bf16 v[50:53], v[174:177], v[182:185], v[50:53]
	v_mfma_f32_16x16x32_bf16 v[42:45], v[166:169], v[190:193], v[42:45]
	v_mfma_f32_16x16x32_bf16 v[34:37], v[174:177], v[190:193], v[34:37]
	v_mfma_f32_16x16x32_bf16 v[26:29], v[166:169], v[198:201], v[26:29]
	v_mfma_f32_16x16x32_bf16 v[18:21], v[174:177], v[198:201], v[18:21]
	v_mfma_f32_16x16x32_bf16 v[10:13], v[166:169], v[212:215], v[10:13]
	v_mfma_f32_16x16x32_bf16 v[2:5], v[174:177], v[212:215], v[2:5]
	s_barrier
	s_setprio 0
.Lpeel_mid_3:
	s_add_i32 s33, 0, 0x18000
	s_add_i32 s55, 0, 0x1c000
	ds_read_b128 v[146:149], v143 offset:32768
	ds_read_b128 v[150:153], v143 offset:33792
	ds_read_b128 v[154:157], v143 offset:34816
	ds_read_b128 v[158:161], v143 offset:35840
	ds_read_b128 v[162:165], v143 offset:49152
	ds_read_b128 v[166:169], v143 offset:50176
	ds_read_b128 v[170:173], v143 offset:51200
	ds_read_b128 v[174:177], v143 offset:52224
	s_add_u32 s0, s22, 0x80000
	s_addc_u32 s1, s23, 0
	s_mov_b32 m0, s29
	ds_read_b128 v[178:181], v145 offset:32768
	ds_read_b128 v[182:185], v145 offset:33792
	ds_read_b128 v[186:189], v145 offset:34816
	ds_read_b128 v[190:193], v145 offset:35840
	ds_read_b128 v[194:197], v145 offset:36864
	ds_read_b128 v[198:201], v145 offset:37888
	ds_read_b128 v[208:211], v145 offset:38912
	ds_read_b128 v[212:215], v145 offset:39936
	global_load_lds_dwordx4 v134, s[0:1]
	s_mov_b32 m0, s30
	s_nop 0
	global_load_lds_dwordx4 v132, s[0:1]
	s_waitcnt vmcnt(8)
	s_waitcnt lgkmcnt(0)
	s_setprio 1
	s_barrier
	v_mfma_f32_16x16x32_bf16 v[126:129], v[146:149], v[178:181], v[126:129]
	v_mfma_f32_16x16x32_bf16 v[118:121], v[154:157], v[178:181], v[118:121]
	v_mfma_f32_16x16x32_bf16 v[110:113], v[146:149], v[186:189], v[110:113]
	v_mfma_f32_16x16x32_bf16 v[102:105], v[154:157], v[186:189], v[102:105]
	v_mfma_f32_16x16x32_bf16 v[94:97], v[146:149], v[194:197], v[94:97]
	v_mfma_f32_16x16x32_bf16 v[86:89], v[154:157], v[194:197], v[86:89]
	v_mfma_f32_16x16x32_bf16 v[78:81], v[146:149], v[208:211], v[78:81]
	v_mfma_f32_16x16x32_bf16 v[70:73], v[154:157], v[208:211], v[70:73]
	v_mfma_f32_16x16x32_bf16 v[126:129], v[150:153], v[182:185], v[126:129]
	v_mfma_f32_16x16x32_bf16 v[118:121], v[158:161], v[182:185], v[118:121]
	v_mfma_f32_16x16x32_bf16 v[110:113], v[150:153], v[190:193], v[110:113]
	v_mfma_f32_16x16x32_bf16 v[102:105], v[158:161], v[190:193], v[102:105]
	v_mfma_f32_16x16x32_bf16 v[94:97], v[150:153], v[198:201], v[94:97]
	v_mfma_f32_16x16x32_bf16 v[86:89], v[158:161], v[198:201], v[86:89]
	v_mfma_f32_16x16x32_bf16 v[78:81], v[150:153], v[212:215], v[78:81]
	v_mfma_f32_16x16x32_bf16 v[70:73], v[158:161], v[212:215], v[70:73]
	v_mfma_f32_16x16x32_bf16 v[122:125], v[162:165], v[178:181], v[122:125]
	v_mfma_f32_16x16x32_bf16 v[114:117], v[170:173], v[178:181], v[114:117]
	v_mfma_f32_16x16x32_bf16 v[106:109], v[162:165], v[186:189], v[106:109]
	v_mfma_f32_16x16x32_bf16 v[98:101], v[170:173], v[186:189], v[98:101]
	v_mfma_f32_16x16x32_bf16 v[90:93], v[162:165], v[194:197], v[90:93]
	v_mfma_f32_16x16x32_bf16 v[82:85], v[170:173], v[194:197], v[82:85]
	v_mfma_f32_16x16x32_bf16 v[74:77], v[162:165], v[208:211], v[74:77]
	v_mfma_f32_16x16x32_bf16 v[66:69], v[170:173], v[208:211], v[66:69]
	v_mfma_f32_16x16x32_bf16 v[122:125], v[166:169], v[182:185], v[122:125]
	v_mfma_f32_16x16x32_bf16 v[114:117], v[174:177], v[182:185], v[114:117]
	v_mfma_f32_16x16x32_bf16 v[106:109], v[166:169], v[190:193], v[106:109]
	v_mfma_f32_16x16x32_bf16 v[98:101], v[174:177], v[190:193], v[98:101]
	v_mfma_f32_16x16x32_bf16 v[90:93], v[166:169], v[198:201], v[90:93]
	v_mfma_f32_16x16x32_bf16 v[82:85], v[174:177], v[198:201], v[82:85]
	v_mfma_f32_16x16x32_bf16 v[74:77], v[166:169], v[212:215], v[74:77]
	v_mfma_f32_16x16x32_bf16 v[66:69], v[174:177], v[212:215], v[66:69]
	s_barrier
	s_setprio 0
	s_add_i32 s0, s33, s26
	s_add_u32 s100, s20, 0x80
	s_addc_u32 s101, s21, 0
	s_mov_b32 m0, s0
	ds_read_b128 v[178:181], v145 offset:49152
	ds_read_b128 v[182:185], v145 offset:50176
	ds_read_b128 v[186:189], v145 offset:51200
	ds_read_b128 v[190:193], v145 offset:52224
	ds_read_b128 v[194:197], v145 offset:53248
	ds_read_b128 v[198:201], v145 offset:54272
	ds_read_b128 v[208:211], v145 offset:55296
	ds_read_b128 v[212:215], v145 offset:56320
	global_load_lds_dwordx4 v202, s[100:101]
	s_add_i32 m0, s0, 0x2000
	s_add_u32 s100, s20, 0x80
	s_addc_u32 s101, s21, 0
	s_add_u32 s0, s20, 0x80080
	s_addc_u32 s1, s21, 0
	s_add_i32 s20, s55, s26
	global_load_lds_dwordx4 v130, s[100:101]
	s_mov_b32 m0, s20
	s_nop 0
	global_load_lds_dwordx4 v202, s[0:1]
	s_add_i32 m0, s20, 0x2000
	s_nop 0
	global_load_lds_dwordx4 v130, s[0:1]
	s_add_u32 s100, s22, 0x80
	s_addc_u32 s101, s23, 0
	s_mov_b32 m0, s31
	s_nop 0
	global_load_lds_dwordx4 v134, s[100:101]
	s_add_u32 s100, s22, 0x80
	s_addc_u32 s101, s23, 0
	s_mov_b32 m0, s34
	s_nop 0
	global_load_lds_dwordx4 v132, s[100:101]
	s_waitcnt vmcnt(8)
	s_waitcnt lgkmcnt(0)
	s_setprio 1
	s_barrier
	v_mfma_f32_16x16x32_bf16 v[62:65], v[146:149], v[178:181], v[62:65]
	v_mfma_f32_16x16x32_bf16 v[54:57], v[154:157], v[178:181], v[54:57]
	v_mfma_f32_16x16x32_bf16 v[46:49], v[146:149], v[186:189], v[46:49]
	v_mfma_f32_16x16x32_bf16 v[38:41], v[154:157], v[186:189], v[38:41]
	v_mfma_f32_16x16x32_bf16 v[30:33], v[146:149], v[194:197], v[30:33]
	v_mfma_f32_16x16x32_bf16 v[22:25], v[154:157], v[194:197], v[22:25]
	v_mfma_f32_16x16x32_bf16 v[14:17], v[146:149], v[208:211], v[14:17]
	v_mfma_f32_16x16x32_bf16 v[6:9], v[154:157], v[208:211], v[6:9]
	v_mfma_f32_16x16x32_bf16 v[62:65], v[150:153], v[182:185], v[62:65]
	v_mfma_f32_16x16x32_bf16 v[54:57], v[158:161], v[182:185], v[54:57]
	v_mfma_f32_16x16x32_bf16 v[46:49], v[150:153], v[190:193], v[46:49]
	v_mfma_f32_16x16x32_bf16 v[38:41], v[158:161], v[190:193], v[38:41]
	v_mfma_f32_16x16x32_bf16 v[30:33], v[150:153], v[198:201], v[30:33]
	v_mfma_f32_16x16x32_bf16 v[22:25], v[158:161], v[198:201], v[22:25]
	v_mfma_f32_16x16x32_bf16 v[14:17], v[150:153], v[212:215], v[14:17]
	v_mfma_f32_16x16x32_bf16 v[6:9], v[158:161], v[212:215], v[6:9]
	v_mfma_f32_16x16x32_bf16 v[58:61], v[162:165], v[178:181], v[58:61]
	v_mfma_f32_16x16x32_bf16 v[50:53], v[170:173], v[178:181], v[50:53]
	v_mfma_f32_16x16x32_bf16 v[42:45], v[162:165], v[186:189], v[42:45]
	v_mfma_f32_16x16x32_bf16 v[34:37], v[170:173], v[186:189], v[34:37]
	v_mfma_f32_16x16x32_bf16 v[26:29], v[162:165], v[194:197], v[26:29]
	v_mfma_f32_16x16x32_bf16 v[18:21], v[170:173], v[194:197], v[18:21]
	v_mfma_f32_16x16x32_bf16 v[10:13], v[162:165], v[208:211], v[10:13]
	v_mfma_f32_16x16x32_bf16 v[2:5], v[170:173], v[208:211], v[2:5]
	v_mfma_f32_16x16x32_bf16 v[58:61], v[166:169], v[182:185], v[58:61]
	v_mfma_f32_16x16x32_bf16 v[50:53], v[174:177], v[182:185], v[50:53]
	v_mfma_f32_16x16x32_bf16 v[42:45], v[166:169], v[190:193], v[42:45]
	v_mfma_f32_16x16x32_bf16 v[34:37], v[174:177], v[190:193], v[34:37]
	v_mfma_f32_16x16x32_bf16 v[26:29], v[166:169], v[198:201], v[26:29]
	v_mfma_f32_16x16x32_bf16 v[18:21], v[174:177], v[198:201], v[18:21]
	v_mfma_f32_16x16x32_bf16 v[10:13], v[166:169], v[212:215], v[10:13]
	v_mfma_f32_16x16x32_bf16 v[2:5], v[174:177], v[212:215], v[2:5]
	s_barrier
	s_setprio 0
	s_add_i32 s59, s59, 2
	s_add_u32 s18, s18, 0x100
	s_addc_u32 s19, s19, 0
	s_add_u32 s49, s49, 0x100
	s_addc_u32 s58, s58, 0
	s_cmp_gt_u32 s59, 29
	s_cbranch_scc0 .LBB0_837
	s_mov_b32 s101, 0x80000001
	s_and_b64 vcc, exec, s[6:7]
	s_cbranch_vccz .LBB0_840
	s_barrier

.LBB0_1588:
	v_lshrrev_b32_e32 v18, 1, v16
	v_and_b32_e32 v18, 24, v18
	v_and_b32_e32 v17, 15, v16
	v_lshlrev_b32_e32 v19, 1, v18
	v_lshlrev_b32_e32 v16, 2, v16
	v_lshl_or_b32 v142, s14, 6, v17
	v_lshl_or_b32 v17, v17, 6, v19
	s_lshl_b32 s0, s14, 13
	v_and_b32_e32 v16, 32, v16
	v_bitop3_b32 v19, v17, s0, v16 bitop3:0xde
	s_lshl_b32 s0, s9, 5
	s_and_b32 s9, s0, 0x60
	s_add_i32 m0, s25, 0x18000
	v_lshl_add_u64 v[8:9], v[8:9], 0, s[80:81]
	s_lshl_b32 s0, s9, 7
	s_waitcnt vmcnt(2)
	s_barrier
	global_load_lds_dwordx4 v[8:9], off
	v_lshl_add_u64 v[6:7], v[6:7], 0, s[80:81]
	s_add_i32 m0, s25, 0x1a000
	s_add_i32 s39, s25, 0x8000
	s_add_i32 s40, s25, 0xa000
	v_bitop3_b32 v143, v17, s0, v16 bitop3:0xde
	v_add_u32_e32 v143, 0x10000, v143
	global_load_lds_dwordx4 v[6:7], off
	v_lshl_add_u64 v[2:3], v[2:3], 0, s[80:81]
	s_mov_b32 m0, s39
	s_add_u32 s0, s2, 0x80080
	global_load_lds_dwordx4 v[2:3], off
	v_lshl_add_u64 v[2:3], v[4:5], 0, s[80:81]
	s_mov_b32 m0, s40
	s_addc_u32 s1, s3, 0
	global_load_lds_dwordx4 v[2:3], off
	s_add_i32 m0, s25, 0x1c000
	v_lshl_add_u64 v[2:3], s[0:1], 0, v[202:203]
	global_load_lds_dwordx4 v[2:3], off
	v_lshl_add_u64 v[2:3], s[0:1], 0, v[130:131]
	s_add_i32 m0, s25, 0x1e000
	s_cmpk_lt_u32 s8, 0x100
	global_load_lds_dwordx4 v[2:3], off
	v_lshlrev_b32_e32 v2, 15, v14
	v_and_b32_e32 v2, 0xffff0000, v2
	v_lshl_add_u32 v2, v13, 12, v2
	v_and_b32_e32 v3, 1, v14
	v_lshl_or_b32 v2, v3, 6, v2
	v_lshl_add_u32 v136, v15, 1, v2
	v_lshlrev_b32_e32 v2, 15, v10
	v_and_b32_e32 v2, 0xffff0000, v2
	s_waitcnt vmcnt(6)
	v_lshl_add_u32 v2, v11, 12, v2
	v_and_b32_e32 v3, 1, v10
	v_lshl_or_b32 v2, v3, 6, v2
	s_cselect_b64 s[14:15], -1, 0
	v_or_b32_e32 v144, s9, v18
	v_mov_b32_e32 v137, v203
	v_lshl_add_u32 v138, v12, 1, v2
	v_mov_b32_e32 v139, v203
	s_mov_b32 s41, 0
	v_add_u32_e32 v145, 0, v19
	s_barrier
	s_waitcnt vmcnt(0)
	s_mov_b32 s101, 0
	s_branch .LBB0_1591

.LBB0_1593:
	s_ashr_i32 s19, s18, 31
	s_lshl_b64 s[0:1], s[18:19], 20
	s_add_u32 s20, s42, s0
	s_addc_u32 s21, s43, s1
	s_and_b64 s[0:1], s[8:9], exec
	s_cselect_b32 s19, s21, s5
	s_cselect_b32 s49, s20, s4
	s_ashr_i32 s17, s16, 31
	s_lshl_b64 s[0:1], s[16:17], 20
	s_add_u32 s22, s30, s0
	s_addc_u32 s23, s31, s1
	s_and_b64 s[0:1], s[8:9], exec
	s_cselect_b32 s17, s23, s3
	s_cselect_b32 s58, s22, s2
	s_add_u32 s28, s4, 0x80080
	s_addc_u32 s29, s5, 0
	s_add_u32 s59, s2, 0x100
	v_mov_b32_e32 v2, 0
	s_addc_u32 s60, s3, 0
	s_mov_b32 s61, -2
	v_mov_b32_e32 v3, v2
	v_pk_mov_b32 v[4:5], v[2:3], v[2:3] op_sel:[0,1]
	v_pk_mov_b32 v[10:11], v[2:3], v[2:3] op_sel:[0,1]
	v_pk_mov_b32 v[12:13], v[2:3], v[2:3] op_sel:[0,1]
	v_pk_mov_b32 v[18:19], v[2:3], v[2:3] op_sel:[0,1]
	v_pk_mov_b32 v[20:21], v[2:3], v[2:3] op_sel:[0,1]
	v_pk_mov_b32 v[26:27], v[2:3], v[2:3] op_sel:[0,1]
	v_pk_mov_b32 v[28:29], v[2:3], v[2:3] op_sel:[0,1]
	v_pk_mov_b32 v[34:35], v[2:3], v[2:3] op_sel:[0,1]
	v_pk_mov_b32 v[36:37], v[2:3], v[2:3] op_sel:[0,1]
	v_pk_mov_b32 v[42:43], v[2:3], v[2:3] op_sel:[0,1]
	v_pk_mov_b32 v[44:45], v[2:3], v[2:3] op_sel:[0,1]
	v_pk_mov_b32 v[50:51], v[2:3], v[2:3] op_sel:[0,1]
	v_pk_mov_b32 v[52:53], v[2:3], v[2:3] op_sel:[0,1]
	v_pk_mov_b32 v[58:59], v[2:3], v[2:3] op_sel:[0,1]
	v_pk_mov_b32 v[60:61], v[2:3], v[2:3] op_sel:[0,1]
	v_pk_mov_b32 v[6:7], v[2:3], v[2:3] op_sel:[0,1]
	v_pk_mov_b32 v[8:9], v[2:3], v[2:3] op_sel:[0,1]
	v_pk_mov_b32 v[14:15], v[2:3], v[2:3] op_sel:[0,1]
	v_pk_mov_b32 v[16:17], v[2:3], v[2:3] op_sel:[0,1]
	v_pk_mov_b32 v[22:23], v[2:3], v[2:3] op_sel:[0,1]
	v_pk_mov_b32 v[24:25], v[2:3], v[2:3] op_sel:[0,1]
	v_pk_mov_b32 v[30:31], v[2:3], v[2:3] op_sel:[0,1]
	v_pk_mov_b32 v[32:33], v[2:3], v[2:3] op_sel:[0,1]
	v_pk_mov_b32 v[38:39], v[2:3], v[2:3] op_sel:[0,1]
	v_pk_mov_b32 v[40:41], v[2:3], v[2:3] op_sel:[0,1]
	v_pk_mov_b32 v[46:47], v[2:3], v[2:3] op_sel:[0,1]
	v_pk_mov_b32 v[48:49], v[2:3], v[2:3] op_sel:[0,1]
	v_pk_mov_b32 v[54:55], v[2:3], v[2:3] op_sel:[0,1]
	v_pk_mov_b32 v[56:57], v[2:3], v[2:3] op_sel:[0,1]
	v_pk_mov_b32 v[62:63], v[2:3], v[2:3] op_sel:[0,1]
	v_pk_mov_b32 v[64:65], v[2:3], v[2:3] op_sel:[0,1]
	v_pk_mov_b32 v[66:67], v[2:3], v[2:3] op_sel:[0,1]
	v_pk_mov_b32 v[68:69], v[2:3], v[2:3] op_sel:[0,1]
	v_pk_mov_b32 v[74:75], v[2:3], v[2:3] op_sel:[0,1]
	v_pk_mov_b32 v[76:77], v[2:3], v[2:3] op_sel:[0,1]
	v_pk_mov_b32 v[82:83], v[2:3], v[2:3] op_sel:[0,1]
	v_pk_mov_b32 v[84:85], v[2:3], v[2:3] op_sel:[0,1]
	v_pk_mov_b32 v[90:91], v[2:3], v[2:3] op_sel:[0,1]
	v_pk_mov_b32 v[92:93], v[2:3], v[2:3] op_sel:[0,1]
	v_pk_mov_b32 v[98:99], v[2:3], v[2:3] op_sel:[0,1]
	v_pk_mov_b32 v[100:101], v[2:3], v[2:3] op_sel:[0,1]
	v_pk_mov_b32 v[106:107], v[2:3], v[2:3] op_sel:[0,1]
	v_pk_mov_b32 v[108:109], v[2:3], v[2:3] op_sel:[0,1]
	v_pk_mov_b32 v[114:115], v[2:3], v[2:3] op_sel:[0,1]
	v_pk_mov_b32 v[116:117], v[2:3], v[2:3] op_sel:[0,1]
	v_pk_mov_b32 v[122:123], v[2:3], v[2:3] op_sel:[0,1]
	v_pk_mov_b32 v[124:125], v[2:3], v[2:3] op_sel:[0,1]
	v_pk_mov_b32 v[70:71], v[2:3], v[2:3] op_sel:[0,1]
	v_pk_mov_b32 v[72:73], v[2:3], v[2:3] op_sel:[0,1]
	v_pk_mov_b32 v[78:79], v[2:3], v[2:3] op_sel:[0,1]
	v_pk_mov_b32 v[80:81], v[2:3], v[2:3] op_sel:[0,1]
	v_pk_mov_b32 v[86:87], v[2:3], v[2:3] op_sel:[0,1]
	v_pk_mov_b32 v[88:89], v[2:3], v[2:3] op_sel:[0,1]
	v_pk_mov_b32 v[94:95], v[2:3], v[2:3] op_sel:[0,1]
	v_pk_mov_b32 v[96:97], v[2:3], v[2:3] op_sel:[0,1]
	v_pk_mov_b32 v[102:103], v[2:3], v[2:3] op_sel:[0,1]
	v_pk_mov_b32 v[104:105], v[2:3], v[2:3] op_sel:[0,1]
	v_pk_mov_b32 v[110:111], v[2:3], v[2:3] op_sel:[0,1]
	v_pk_mov_b32 v[112:113], v[2:3], v[2:3] op_sel:[0,1]
	v_pk_mov_b32 v[118:119], v[2:3], v[2:3] op_sel:[0,1]
	v_pk_mov_b32 v[120:121], v[2:3], v[2:3] op_sel:[0,1]
	v_pk_mov_b32 v[126:127], v[2:3], v[2:3] op_sel:[0,1]
	v_pk_mov_b32 v[128:129], v[2:3], v[2:3] op_sel:[0,1]
	s_cmp_eq_u32 s101, 0x80000001
	s_cbranch_scc0 .LBB0_1594
	s_add_u32 s0, s28, 0xfff80080
	s_addc_u32 s1, s29, -1
	s_add_i32 s33, 0, 0x10000
	s_cmp_eq_u32 s61, 28
	s_cselect_b32 s5, s19, s1
	s_cselect_b32 s4, s49, s0
	s_cselect_b32 s3, s17, s60
	s_cselect_b32 s2, s58, s59
	s_add_i32 s55, 0, 0x14000
	ds_read_b128 v[146:149], v143
	ds_read_b128 v[150:153], v143 offset:1024
	ds_read_b128 v[154:157], v143 offset:2048
	ds_read_b128 v[158:161], v143 offset:3072
	ds_read_b128 v[162:165], v143 offset:16384
	ds_read_b128 v[166:169], v143 offset:17408
	ds_read_b128 v[170:173], v143 offset:18432
	ds_read_b128 v[174:177], v143 offset:19456
	s_add_i32 m0, s25, 0xc000
	ds_read_b128 v[178:181], v145
	ds_read_b128 v[182:185], v145 offset:1024
	ds_read_b128 v[186:189], v145 offset:2048
	ds_read_b128 v[190:193], v145 offset:3072
	ds_read_b128 v[194:197], v145 offset:4096
	ds_read_b128 v[198:201], v145 offset:5120
	ds_read_b128 v[208:211], v145 offset:6144
	ds_read_b128 v[212:215], v145 offset:7168
	global_load_lds_dwordx4 v136, s[28:29]
	s_add_i32 m0, s25, 0xe000
	s_nop 0
	global_load_lds_dwordx4 v138, s[28:29]
	s_waitcnt vmcnt(16)
	s_waitcnt lgkmcnt(0)
	s_setprio 1
	s_barrier
	v_mfma_f32_16x16x32_bf16 v[126:129], v[146:149], v[178:181], v[126:129]
	v_mfma_f32_16x16x32_bf16 v[118:121], v[154:157], v[178:181], v[118:121]
	v_mfma_f32_16x16x32_bf16 v[110:113], v[146:149], v[186:189], v[110:113]
	v_mfma_f32_16x16x32_bf16 v[102:105], v[154:157], v[186:189], v[102:105]
	v_mfma_f32_16x16x32_bf16 v[94:97], v[146:149], v[194:197], v[94:97]
	v_mfma_f32_16x16x32_bf16 v[86:89], v[154:157], v[194:197], v[86:89]
	v_mfma_f32_16x16x32_bf16 v[78:81], v[146:149], v[208:211], v[78:81]
	v_mfma_f32_16x16x32_bf16 v[70:73], v[154:157], v[208:211], v[70:73]
	v_mfma_f32_16x16x32_bf16 v[126:129], v[150:153], v[182:185], v[126:129]
	v_mfma_f32_16x16x32_bf16 v[118:121], v[158:161], v[182:185], v[118:121]
	v_mfma_f32_16x16x32_bf16 v[110:113], v[150:153], v[190:193], v[110:113]
	v_mfma_f32_16x16x32_bf16 v[102:105], v[158:161], v[190:193], v[102:105]
	v_mfma_f32_16x16x32_bf16 v[94:97], v[150:153], v[198:201], v[94:97]
	v_mfma_f32_16x16x32_bf16 v[86:89], v[158:161], v[198:201], v[86:89]
	v_mfma_f32_16x16x32_bf16 v[78:81], v[150:153], v[212:215], v[78:81]
	v_mfma_f32_16x16x32_bf16 v[70:73], v[158:161], v[212:215], v[70:73]
	v_mfma_f32_16x16x32_bf16 v[122:125], v[162:165], v[178:181], v[122:125]
	v_mfma_f32_16x16x32_bf16 v[114:117], v[170:173], v[178:181], v[114:117]
	v_mfma_f32_16x16x32_bf16 v[106:109], v[162:165], v[186:189], v[106:109]
	v_mfma_f32_16x16x32_bf16 v[98:101], v[170:173], v[186:189], v[98:101]
	v_mfma_f32_16x16x32_bf16 v[90:93], v[162:165], v[194:197], v[90:93]
	v_mfma_f32_16x16x32_bf16 v[82:85], v[170:173], v[194:197], v[82:85]
	v_mfma_f32_16x16x32_bf16 v[74:77], v[162:165], v[208:211], v[74:77]
	v_mfma_f32_16x16x32_bf16 v[66:69], v[170:173], v[208:211], v[66:69]
	v_mfma_f32_16x16x32_bf16 v[122:125], v[166:169], v[182:185], v[122:125]
	v_mfma_f32_16x16x32_bf16 v[114:117], v[174:177], v[182:185], v[114:117]
	v_mfma_f32_16x16x32_bf16 v[106:109], v[166:169], v[190:193], v[106:109]
	v_mfma_f32_16x16x32_bf16 v[98:101], v[174:177], v[190:193], v[98:101]
	v_mfma_f32_16x16x32_bf16 v[90:93], v[166:169], v[198:201], v[90:93]
	v_mfma_f32_16x16x32_bf16 v[82:85], v[174:177], v[198:201], v[82:85]
	v_mfma_f32_16x16x32_bf16 v[74:77], v[166:169], v[212:215], v[74:77]
	v_mfma_f32_16x16x32_bf16 v[66:69], v[174:177], v[212:215], v[66:69]
	s_barrier
	s_setprio 0
	s_add_i32 s0, s33, s36
	s_mov_b32 m0, s0
	ds_read_b128 v[178:181], v145 offset:16384
	ds_read_b128 v[182:185], v145 offset:17408
	ds_read_b128 v[186:189], v145 offset:18432
	ds_read_b128 v[190:193], v145 offset:19456
	ds_read_b128 v[194:197], v145 offset:20480
	ds_read_b128 v[198:201], v145 offset:21504
	ds_read_b128 v[208:211], v145 offset:22528
	ds_read_b128 v[212:215], v145 offset:23552
	global_load_lds_dwordx4 v202, s[2:3]
	s_add_i32 m0, s0, 0x2000
	s_add_u32 s0, s2, 0x80000
	s_addc_u32 s1, s3, 0
	s_add_i32 s33, s55, s36
	global_load_lds_dwordx4 v130, s[2:3]
	s_mov_b32 m0, s33
	s_nop 0
	global_load_lds_dwordx4 v202, s[0:1]
	s_add_i32 m0, s33, 0x2000
	s_nop 0
	global_load_lds_dwordx4 v130, s[0:1]
	s_mov_b32 m0, s25
	s_nop 0
	global_load_lds_dwordx4 v134, s[4:5]
	s_mov_b32 m0, s27
	s_nop 0
	global_load_lds_dwordx4 v132, s[4:5]
	s_waitcnt vmcnt(16)
	s_waitcnt lgkmcnt(0)
	s_setprio 1
	s_barrier
	v_mfma_f32_16x16x32_bf16 v[62:65], v[146:149], v[178:181], v[62:65]
	v_mfma_f32_16x16x32_bf16 v[54:57], v[154:157], v[178:181], v[54:57]
	v_mfma_f32_16x16x32_bf16 v[46:49], v[146:149], v[186:189], v[46:49]
	v_mfma_f32_16x16x32_bf16 v[38:41], v[154:157], v[186:189], v[38:41]
	v_mfma_f32_16x16x32_bf16 v[30:33], v[146:149], v[194:197], v[30:33]
	v_mfma_f32_16x16x32_bf16 v[22:25], v[154:157], v[194:197], v[22:25]
	v_mfma_f32_16x16x32_bf16 v[14:17], v[146:149], v[208:211], v[14:17]
	v_mfma_f32_16x16x32_bf16 v[6:9], v[154:157], v[208:211], v[6:9]
	v_mfma_f32_16x16x32_bf16 v[62:65], v[150:153], v[182:185], v[62:65]
	v_mfma_f32_16x16x32_bf16 v[54:57], v[158:161], v[182:185], v[54:57]
	v_mfma_f32_16x16x32_bf16 v[46:49], v[150:153], v[190:193], v[46:49]
	v_mfma_f32_16x16x32_bf16 v[38:41], v[158:161], v[190:193], v[38:41]
	v_mfma_f32_16x16x32_bf16 v[30:33], v[150:153], v[198:201], v[30:33]
	v_mfma_f32_16x16x32_bf16 v[22:25], v[158:161], v[198:201], v[22:25]
	v_mfma_f32_16x16x32_bf16 v[14:17], v[150:153], v[212:215], v[14:17]
	v_mfma_f32_16x16x32_bf16 v[6:9], v[158:161], v[212:215], v[6:9]
	v_mfma_f32_16x16x32_bf16 v[58:61], v[162:165], v[178:181], v[58:61]
	v_mfma_f32_16x16x32_bf16 v[50:53], v[170:173], v[178:181], v[50:53]
	v_mfma_f32_16x16x32_bf16 v[42:45], v[162:165], v[186:189], v[42:45]
	v_mfma_f32_16x16x32_bf16 v[34:37], v[170:173], v[186:189], v[34:37]
	v_mfma_f32_16x16x32_bf16 v[26:29], v[162:165], v[194:197], v[26:29]
	v_mfma_f32_16x16x32_bf16 v[18:21], v[170:173], v[194:197], v[18:21]
	v_mfma_f32_16x16x32_bf16 v[10:13], v[162:165], v[208:211], v[10:13]
	v_mfma_f32_16x16x32_bf16 v[2:5], v[170:173], v[208:211], v[2:5]
	v_mfma_f32_16x16x32_bf16 v[58:61], v[166:169], v[182:185], v[58:61]
	v_mfma_f32_16x16x32_bf16 v[50:53], v[174:177], v[182:185], v[50:53]
	v_mfma_f32_16x16x32_bf16 v[42:45], v[166:169], v[190:193], v[42:45]
	v_mfma_f32_16x16x32_bf16 v[34:37], v[174:177], v[190:193], v[34:37]
	v_mfma_f32_16x16x32_bf16 v[26:29], v[166:169], v[198:201], v[26:29]
	v_mfma_f32_16x16x32_bf16 v[18:21], v[174:177], v[198:201], v[18:21]
	v_mfma_f32_16x16x32_bf16 v[10:13], v[166:169], v[212:215], v[10:13]
	v_mfma_f32_16x16x32_bf16 v[2:5], v[174:177], v[212:215], v[2:5]
	s_barrier
	s_setprio 0
	s_branch .Lpeel_mid_10
.LBB0_1594:
	s_add_u32 s0, s28, 0xfff80080
	s_addc_u32 s1, s29, -1
	s_add_i32 s33, 0, 0x10000
	s_cmp_eq_u32 s61, 28
	s_cselect_b32 s5, s19, s1
	s_cselect_b32 s4, s49, s0
	s_cselect_b32 s3, s17, s60
	s_cselect_b32 s2, s58, s59
	s_add_i32 s55, 0, 0x14000
	ds_read_b128 v[146:149], v143
	ds_read_b128 v[150:153], v143 offset:1024
	ds_read_b128 v[154:157], v143 offset:2048
	ds_read_b128 v[158:161], v143 offset:3072
	ds_read_b128 v[162:165], v143 offset:16384
	ds_read_b128 v[166:169], v143 offset:17408
	ds_read_b128 v[170:173], v143 offset:18432
	ds_read_b128 v[174:177], v143 offset:19456
	s_add_i32 m0, s25, 0xc000
	ds_read_b128 v[178:181], v145
	ds_read_b128 v[182:185], v145 offset:1024
	ds_read_b128 v[186:189], v145 offset:2048
	ds_read_b128 v[190:193], v145 offset:3072
	ds_read_b128 v[194:197], v145 offset:4096
	ds_read_b128 v[198:201], v145 offset:5120
	ds_read_b128 v[208:211], v145 offset:6144
	ds_read_b128 v[212:215], v145 offset:7168
	global_load_lds_dwordx4 v136, s[28:29]
	s_add_i32 m0, s25, 0xe000
	s_nop 0
	global_load_lds_dwordx4 v138, s[28:29]
	s_waitcnt vmcnt(8)
	s_waitcnt lgkmcnt(0)
	s_setprio 1
	s_barrier
	v_mfma_f32_16x16x32_bf16 v[126:129], v[146:149], v[178:181], v[126:129]
	v_mfma_f32_16x16x32_bf16 v[118:121], v[154:157], v[178:181], v[118:121]
	v_mfma_f32_16x16x32_bf16 v[110:113], v[146:149], v[186:189], v[110:113]
	v_mfma_f32_16x16x32_bf16 v[102:105], v[154:157], v[186:189], v[102:105]
	v_mfma_f32_16x16x32_bf16 v[94:97], v[146:149], v[194:197], v[94:97]
	v_mfma_f32_16x16x32_bf16 v[86:89], v[154:157], v[194:197], v[86:89]
	v_mfma_f32_16x16x32_bf16 v[78:81], v[146:149], v[208:211], v[78:81]
	v_mfma_f32_16x16x32_bf16 v[70:73], v[154:157], v[208:211], v[70:73]
	v_mfma_f32_16x16x32_bf16 v[126:129], v[150:153], v[182:185], v[126:129]
	v_mfma_f32_16x16x32_bf16 v[118:121], v[158:161], v[182:185], v[118:121]
	v_mfma_f32_16x16x32_bf16 v[110:113], v[150:153], v[190:193], v[110:113]
	v_mfma_f32_16x16x32_bf16 v[102:105], v[158:161], v[190:193], v[102:105]
	v_mfma_f32_16x16x32_bf16 v[94:97], v[150:153], v[198:201], v[94:97]
	v_mfma_f32_16x16x32_bf16 v[86:89], v[158:161], v[198:201], v[86:89]
	v_mfma_f32_16x16x32_bf16 v[78:81], v[150:153], v[212:215], v[78:81]
	v_mfma_f32_16x16x32_bf16 v[70:73], v[158:161], v[212:215], v[70:73]
	v_mfma_f32_16x16x32_bf16 v[122:125], v[162:165], v[178:181], v[122:125]
	v_mfma_f32_16x16x32_bf16 v[114:117], v[170:173], v[178:181], v[114:117]
	v_mfma_f32_16x16x32_bf16 v[106:109], v[162:165], v[186:189], v[106:109]
	v_mfma_f32_16x16x32_bf16 v[98:101], v[170:173], v[186:189], v[98:101]
	v_mfma_f32_16x16x32_bf16 v[90:93], v[162:165], v[194:197], v[90:93]
	v_mfma_f32_16x16x32_bf16 v[82:85], v[170:173], v[194:197], v[82:85]
	v_mfma_f32_16x16x32_bf16 v[74:77], v[162:165], v[208:211], v[74:77]
	v_mfma_f32_16x16x32_bf16 v[66:69], v[170:173], v[208:211], v[66:69]
	v_mfma_f32_16x16x32_bf16 v[122:125], v[166:169], v[182:185], v[122:125]
	v_mfma_f32_16x16x32_bf16 v[114:117], v[174:177], v[182:185], v[114:117]
	v_mfma_f32_16x16x32_bf16 v[106:109], v[166:169], v[190:193], v[106:109]
	v_mfma_f32_16x16x32_bf16 v[98:101], v[174:177], v[190:193], v[98:101]
	v_mfma_f32_16x16x32_bf16 v[90:93], v[166:169], v[198:201], v[90:93]
	v_mfma_f32_16x16x32_bf16 v[82:85], v[174:177], v[198:201], v[82:85]
	v_mfma_f32_16x16x32_bf16 v[74:77], v[166:169], v[212:215], v[74:77]
	v_mfma_f32_16x16x32_bf16 v[66:69], v[174:177], v[212:215], v[66:69]
	s_barrier
	s_setprio 0
	s_add_i32 s0, s33, s36
	s_mov_b32 m0, s0
	ds_read_b128 v[178:181], v145 offset:16384
	ds_read_b128 v[182:185], v145 offset:17408
	ds_read_b128 v[186:189], v145 offset:18432
	ds_read_b128 v[190:193], v145 offset:19456
	ds_read_b128 v[194:197], v145 offset:20480
	ds_read_b128 v[198:201], v145 offset:21504
	ds_read_b128 v[208:211], v145 offset:22528
	ds_read_b128 v[212:215], v145 offset:23552
	global_load_lds_dwordx4 v202, s[2:3]
	s_add_i32 m0, s0, 0x2000
	s_add_u32 s0, s2, 0x80000
	s_addc_u32 s1, s3, 0
	s_add_i32 s33, s55, s36
	global_load_lds_dwordx4 v130, s[2:3]
	s_mov_b32 m0, s33
	s_nop 0
	global_load_lds_dwordx4 v202, s[0:1]
	s_add_i32 m0, s33, 0x2000
	s_nop 0
	global_load_lds_dwordx4 v130, s[0:1]
	s_mov_b32 m0, s25
	s_nop 0
	global_load_lds_dwordx4 v134, s[4:5]
	s_mov_b32 m0, s27
	s_nop 0
	global_load_lds_dwordx4 v132, s[4:5]
	s_waitcnt vmcnt(8)
	s_waitcnt lgkmcnt(0)
	s_setprio 1
	s_barrier
	v_mfma_f32_16x16x32_bf16 v[62:65], v[146:149], v[178:181], v[62:65]
	v_mfma_f32_16x16x32_bf16 v[54:57], v[154:157], v[178:181], v[54:57]
	v_mfma_f32_16x16x32_bf16 v[46:49], v[146:149], v[186:189], v[46:49]
	v_mfma_f32_16x16x32_bf16 v[38:41], v[154:157], v[186:189], v[38:41]
	v_mfma_f32_16x16x32_bf16 v[30:33], v[146:149], v[194:197], v[30:33]
	v_mfma_f32_16x16x32_bf16 v[22:25], v[154:157], v[194:197], v[22:25]
	v_mfma_f32_16x16x32_bf16 v[14:17], v[146:149], v[208:211], v[14:17]
	v_mfma_f32_16x16x32_bf16 v[6:9], v[154:157], v[208:211], v[6:9]
	v_mfma_f32_16x16x32_bf16 v[62:65], v[150:153], v[182:185], v[62:65]
	v_mfma_f32_16x16x32_bf16 v[54:57], v[158:161], v[182:185], v[54:57]
	v_mfma_f32_16x16x32_bf16 v[46:49], v[150:153], v[190:193], v[46:49]
	v_mfma_f32_16x16x32_bf16 v[38:41], v[158:161], v[190:193], v[38:41]
	v_mfma_f32_16x16x32_bf16 v[30:33], v[150:153], v[198:201], v[30:33]
	v_mfma_f32_16x16x32_bf16 v[22:25], v[158:161], v[198:201], v[22:25]
	v_mfma_f32_16x16x32_bf16 v[14:17], v[150:153], v[212:215], v[14:17]
	v_mfma_f32_16x16x32_bf16 v[6:9], v[158:161], v[212:215], v[6:9]
	v_mfma_f32_16x16x32_bf16 v[58:61], v[162:165], v[178:181], v[58:61]
	v_mfma_f32_16x16x32_bf16 v[50:53], v[170:173], v[178:181], v[50:53]
	v_mfma_f32_16x16x32_bf16 v[42:45], v[162:165], v[186:189], v[42:45]
	v_mfma_f32_16x16x32_bf16 v[34:37], v[170:173], v[186:189], v[34:37]
	v_mfma_f32_16x16x32_bf16 v[26:29], v[162:165], v[194:197], v[26:29]
	v_mfma_f32_16x16x32_bf16 v[18:21], v[170:173], v[194:197], v[18:21]
	v_mfma_f32_16x16x32_bf16 v[10:13], v[162:165], v[208:211], v[10:13]
	v_mfma_f32_16x16x32_bf16 v[2:5], v[170:173], v[208:211], v[2:5]
	v_mfma_f32_16x16x32_bf16 v[58:61], v[166:169], v[182:185], v[58:61]
	v_mfma_f32_16x16x32_bf16 v[50:53], v[174:177], v[182:185], v[50:53]
	v_mfma_f32_16x16x32_bf16 v[42:45], v[166:169], v[190:193], v[42:45]
	v_mfma_f32_16x16x32_bf16 v[34:37], v[174:177], v[190:193], v[34:37]
	v_mfma_f32_16x16x32_bf16 v[26:29], v[166:169], v[198:201], v[26:29]
	v_mfma_f32_16x16x32_bf16 v[18:21], v[174:177], v[198:201], v[18:21]
	v_mfma_f32_16x16x32_bf16 v[10:13], v[166:169], v[212:215], v[10:13]
	v_mfma_f32_16x16x32_bf16 v[2:5], v[174:177], v[212:215], v[2:5]
	s_barrier
	s_setprio 0
.Lpeel_mid_10:
	s_add_i32 s33, 0, 0x18000
	s_add_i32 s55, 0, 0x1c000
	ds_read_b128 v[146:149], v143 offset:32768
	ds_read_b128 v[150:153], v143 offset:33792
	ds_read_b128 v[154:157], v143 offset:34816
	ds_read_b128 v[158:161], v143 offset:35840
	ds_read_b128 v[162:165], v143 offset:49152
	ds_read_b128 v[166:169], v143 offset:50176
	ds_read_b128 v[170:173], v143 offset:51200
	ds_read_b128 v[174:177], v143 offset:52224
	s_add_u32 s0, s4, 0x80000
	s_addc_u32 s1, s5, 0
	s_mov_b32 m0, s37
	ds_read_b128 v[178:181], v145 offset:32768
	ds_read_b128 v[182:185], v145 offset:33792
	ds_read_b128 v[186:189], v145 offset:34816
	ds_read_b128 v[190:193], v145 offset:35840
	ds_read_b128 v[194:197], v145 offset:36864
	ds_read_b128 v[198:201], v145 offset:37888
	ds_read_b128 v[208:211], v145 offset:38912
	ds_read_b128 v[212:215], v145 offset:39936
	global_load_lds_dwordx4 v134, s[0:1]
	s_mov_b32 m0, s38
	s_nop 0
	global_load_lds_dwordx4 v132, s[0:1]
	s_waitcnt vmcnt(8)
	s_waitcnt lgkmcnt(0)
	s_setprio 1
	s_barrier
	v_mfma_f32_16x16x32_bf16 v[126:129], v[146:149], v[178:181], v[126:129]
	v_mfma_f32_16x16x32_bf16 v[118:121], v[154:157], v[178:181], v[118:121]
	v_mfma_f32_16x16x32_bf16 v[110:113], v[146:149], v[186:189], v[110:113]
	v_mfma_f32_16x16x32_bf16 v[102:105], v[154:157], v[186:189], v[102:105]
	v_mfma_f32_16x16x32_bf16 v[94:97], v[146:149], v[194:197], v[94:97]
	v_mfma_f32_16x16x32_bf16 v[86:89], v[154:157], v[194:197], v[86:89]
	v_mfma_f32_16x16x32_bf16 v[78:81], v[146:149], v[208:211], v[78:81]
	v_mfma_f32_16x16x32_bf16 v[70:73], v[154:157], v[208:211], v[70:73]
	v_mfma_f32_16x16x32_bf16 v[126:129], v[150:153], v[182:185], v[126:129]
	v_mfma_f32_16x16x32_bf16 v[118:121], v[158:161], v[182:185], v[118:121]
	v_mfma_f32_16x16x32_bf16 v[110:113], v[150:153], v[190:193], v[110:113]
	v_mfma_f32_16x16x32_bf16 v[102:105], v[158:161], v[190:193], v[102:105]
	v_mfma_f32_16x16x32_bf16 v[94:97], v[150:153], v[198:201], v[94:97]
	v_mfma_f32_16x16x32_bf16 v[86:89], v[158:161], v[198:201], v[86:89]
	v_mfma_f32_16x16x32_bf16 v[78:81], v[150:153], v[212:215], v[78:81]
	v_mfma_f32_16x16x32_bf16 v[70:73], v[158:161], v[212:215], v[70:73]
	v_mfma_f32_16x16x32_bf16 v[122:125], v[162:165], v[178:181], v[122:125]
	v_mfma_f32_16x16x32_bf16 v[114:117], v[170:173], v[178:181], v[114:117]
	v_mfma_f32_16x16x32_bf16 v[106:109], v[162:165], v[186:189], v[106:109]
	v_mfma_f32_16x16x32_bf16 v[98:101], v[170:173], v[186:189], v[98:101]
	v_mfma_f32_16x16x32_bf16 v[90:93], v[162:165], v[194:197], v[90:93]
	v_mfma_f32_16x16x32_bf16 v[82:85], v[170:173], v[194:197], v[82:85]
	v_mfma_f32_16x16x32_bf16 v[74:77], v[162:165], v[208:211], v[74:77]
	v_mfma_f32_16x16x32_bf16 v[66:69], v[170:173], v[208:211], v[66:69]
	v_mfma_f32_16x16x32_bf16 v[122:125], v[166:169], v[182:185], v[122:125]
	v_mfma_f32_16x16x32_bf16 v[114:117], v[174:177], v[182:185], v[114:117]
	v_mfma_f32_16x16x32_bf16 v[106:109], v[166:169], v[190:193], v[106:109]
	v_mfma_f32_16x16x32_bf16 v[98:101], v[174:177], v[190:193], v[98:101]
	v_mfma_f32_16x16x32_bf16 v[90:93], v[166:169], v[198:201], v[90:93]
	v_mfma_f32_16x16x32_bf16 v[82:85], v[174:177], v[198:201], v[82:85]
	v_mfma_f32_16x16x32_bf16 v[74:77], v[166:169], v[212:215], v[74:77]
	v_mfma_f32_16x16x32_bf16 v[66:69], v[174:177], v[212:215], v[66:69]
	s_barrier
	s_setprio 0
	s_add_i32 s0, s33, s36
	s_add_u32 s100, s2, 0x80
	s_addc_u32 s101, s3, 0
	s_mov_b32 m0, s0
	ds_read_b128 v[178:181], v145 offset:49152
	ds_read_b128 v[182:185], v145 offset:50176
	ds_read_b128 v[186:189], v145 offset:51200
	ds_read_b128 v[190:193], v145 offset:52224
	ds_read_b128 v[194:197], v145 offset:53248
	ds_read_b128 v[198:201], v145 offset:54272
	ds_read_b128 v[208:211], v145 offset:55296
	ds_read_b128 v[212:215], v145 offset:56320
	global_load_lds_dwordx4 v202, s[100:101]
	s_add_i32 m0, s0, 0x2000
	s_add_u32 s100, s2, 0x80
	s_addc_u32 s101, s3, 0
	s_add_u32 s0, s2, 0x80080
	s_addc_u32 s1, s3, 0
	s_add_i32 s2, s55, s36
	global_load_lds_dwordx4 v130, s[100:101]
	s_mov_b32 m0, s2
	s_nop 0
	global_load_lds_dwordx4 v202, s[0:1]
	s_add_i32 m0, s2, 0x2000
	s_nop 0
	global_load_lds_dwordx4 v130, s[0:1]
	s_add_u32 s100, s4, 0x80
	s_addc_u32 s101, s5, 0
	s_mov_b32 m0, s39
	s_nop 0
	global_load_lds_dwordx4 v134, s[100:101]
	s_add_u32 s100, s4, 0x80
	s_addc_u32 s101, s5, 0
	s_mov_b32 m0, s40
	s_nop 0
	global_load_lds_dwordx4 v132, s[100:101]
	s_waitcnt vmcnt(8)
	s_waitcnt lgkmcnt(0)
	s_setprio 1
	s_barrier
	v_mfma_f32_16x16x32_bf16 v[62:65], v[146:149], v[178:181], v[62:65]
	v_mfma_f32_16x16x32_bf16 v[54:57], v[154:157], v[178:181], v[54:57]
	v_mfma_f32_16x16x32_bf16 v[46:49], v[146:149], v[186:189], v[46:49]
	v_mfma_f32_16x16x32_bf16 v[38:41], v[154:157], v[186:189], v[38:41]
	v_mfma_f32_16x16x32_bf16 v[30:33], v[146:149], v[194:197], v[30:33]
	v_mfma_f32_16x16x32_bf16 v[22:25], v[154:157], v[194:197], v[22:25]
	v_mfma_f32_16x16x32_bf16 v[14:17], v[146:149], v[208:211], v[14:17]
	v_mfma_f32_16x16x32_bf16 v[6:9], v[154:157], v[208:211], v[6:9]
	v_mfma_f32_16x16x32_bf16 v[62:65], v[150:153], v[182:185], v[62:65]
	v_mfma_f32_16x16x32_bf16 v[54:57], v[158:161], v[182:185], v[54:57]
	v_mfma_f32_16x16x32_bf16 v[46:49], v[150:153], v[190:193], v[46:49]
	v_mfma_f32_16x16x32_bf16 v[38:41], v[158:161], v[190:193], v[38:41]
	v_mfma_f32_16x16x32_bf16 v[30:33], v[150:153], v[198:201], v[30:33]
	v_mfma_f32_16x16x32_bf16 v[22:25], v[158:161], v[198:201], v[22:25]
	v_mfma_f32_16x16x32_bf16 v[14:17], v[150:153], v[212:215], v[14:17]
	v_mfma_f32_16x16x32_bf16 v[6:9], v[158:161], v[212:215], v[6:9]
	v_mfma_f32_16x16x32_bf16 v[58:61], v[162:165], v[178:181], v[58:61]
	v_mfma_f32_16x16x32_bf16 v[50:53], v[170:173], v[178:181], v[50:53]
	v_mfma_f32_16x16x32_bf16 v[42:45], v[162:165], v[186:189], v[42:45]
	v_mfma_f32_16x16x32_bf16 v[34:37], v[170:173], v[186:189], v[34:37]
	v_mfma_f32_16x16x32_bf16 v[26:29], v[162:165], v[194:197], v[26:29]
	v_mfma_f32_16x16x32_bf16 v[18:21], v[170:173], v[194:197], v[18:21]
	v_mfma_f32_16x16x32_bf16 v[10:13], v[162:165], v[208:211], v[10:13]
	v_mfma_f32_16x16x32_bf16 v[2:5], v[170:173], v[208:211], v[2:5]
	v_mfma_f32_16x16x32_bf16 v[58:61], v[166:169], v[182:185], v[58:61]
	v_mfma_f32_16x16x32_bf16 v[50:53], v[174:177], v[182:185], v[50:53]
	v_mfma_f32_16x16x32_bf16 v[42:45], v[166:169], v[190:193], v[42:45]
	v_mfma_f32_16x16x32_bf16 v[34:37], v[174:177], v[190:193], v[34:37]
	v_mfma_f32_16x16x32_bf16 v[26:29], v[166:169], v[198:201], v[26:29]
	v_mfma_f32_16x16x32_bf16 v[18:21], v[174:177], v[198:201], v[18:21]
	v_mfma_f32_16x16x32_bf16 v[10:13], v[166:169], v[212:215], v[10:13]
	v_mfma_f32_16x16x32_bf16 v[2:5], v[174:177], v[212:215], v[2:5]
	s_barrier
	s_setprio 0
	s_add_i32 s61, s61, 2
	s_add_u32 s28, s28, 0x100
	s_addc_u32 s29, s29, 0
	s_add_u32 s59, s59, 0x100
	s_addc_u32 s60, s60, 0
	s_cmp_gt_u32 s61, 29
	s_cbranch_scc0 .LBB0_1594
	s_mov_b32 s101, 0x80000001
	s_and_b64 vcc, exec, s[14:15]
	s_cbranch_vccz .LBB0_1597
	s_barrier
